# FFN1 epilogue pipelined across the two wave rows: one workgroup barrier per epilogue quarter (rows run one barrier apart)
# speedup vs baseline: 1.0121x; 1.0121x over previous
; #define LAS __attribute__((address_space(3)))
; __device__ __forceinline__ float sigmoidf_(float x) { return __builtin_amdgcn_rcpf(1.0f + __expf(-x)); }
;     __device__ __forceinline__ void operator()(AccRef acc, const Unit& u, int wr, int wc, int fr, int fq) const {
;     ...
;                 f32x4 h2v = (f32x4){0.f, 0.f, 0.f, 0.f}, h3v = h2v, h2g = h2v, h3g = h2v;
;                 const int pb = ai * 2 + wr - 1;
;                 if (pb >= 0 && fr == 0) { const LAS float* xp = xch + (pb * 2) * 256 + clb + 4 * n;
;                     h2v = *(const LAS f32x4*)(xp); h3v = *(const LAS f32x4*)(xp + 256); h2g = *(const LAS f32x4*)(xp + 128); h3g = *(const LAS f32x4*)(xp + 256 + 128); }
;                 float o[4][4];
; #pragma unroll
;                 for (int j = 0; j < 4; ++j) {
;                     const float v0 = acc[ai][0][0][n][j], v1 = acc[ai][0][1][n][j], v2 = acc[ai][0][2][n][j], v3 = acc[ai][0][3][n][j];
;                     const float g0 = acc[ai][1][0][n][j], g1 = acc[ai][1][1][n][j], g2 = acc[ai][1][2][n][j], g3 = acc[ai][1][3][n][j];
;                     const float pv3 = dpp_upd<0x111>(h3v[j], v3), pv2 = dpp_upd<0x111>(h2v[j], v2), pg3 = dpp_upd<0x111>(h3g[j], g3), pg2 = dpp_upd<0x111>(h2g[j], g2);
;                     const float hv0 = bvv[j] + w2v[j] * v0 + w1v[j] * pv3 + w0v[j] * pv2, hv1 = bvv[j] + w2v[j] * v1 + w1v[j] * v0 + w0v[j] * pv3;
;                     const float hv2 = bvv[j] + w2v[j] * v2 + w1v[j] * v1 + w0v[j] * v0, hv3 = bvv[j] + w2v[j] * v3 + w1v[j] * v2 + w0v[j] * v1;
;                     const float hg0 = bvg[j] + w2g[j] * g0 + w1g[j] * pg3 + w0g[j] * pg2, hg1 = bvg[j] + w2g[j] * g1 + w1g[j] * g0 + w0g[j] * pg3;
;                     const float hg2 = bvg[j] + w2g[j] * g2 + w1g[j] * g1 + w0g[j] * g0, hg3 = bvg[j] + w2g[j] * g3 + w1g[j] * g2 + w0g[j] * g1;
;                     o[0][j] = hg0 * sigmoidf_(hg0) * hv0; o[1][j] = hg1 * sigmoidf_(hg1) * hv1; o[2][j] = hg2 * sigmoidf_(hg2) * hv2; o[3][j] = hg3 * sigmoidf_(hg3) * hv3; }
; #pragma unroll
;                 for (int m = 0; m < 4; ++m) { u32x2 w; w.x = cvt_pk_bf16(o[m][0], o[m][1]); w.y = cvt_pk_bf16(o[m][2], o[m][3]);
;                     *(u32x2*)(Aout + (size_t)(row0 + ai * 128 + m) * FH + hc0 + 4 * n) = w; } } }
.LBB0_316:
	s_or_b64 exec, exec, s[40:41]
	v_pk_fma_f32 v[248:249], v[152:153], v[184:185], v[188:189]
	v_mov_b32_dpp v206, v128 row_shr:1 row_mask:0xf bank_mask:0xf
	v_mov_b32_dpp v207, v129 row_shr:1 row_mask:0xf bank_mask:0xf
	v_pk_fma_f32 v[248:249], v[180:181], v[198:199], v[248:249]
	v_mov_b32_dpp v194, v148 row_shr:1 row_mask:0xf bank_mask:0xf
	v_pk_fma_f32 v[206:207], v[176:177], v[206:207], v[248:249]
	v_mov_b32_dpp v195, v149 row_shr:1 row_mask:0xf bank_mask:0xf
	v_exp_f32_e32 v248, v206
	v_exp_f32_e32 v249, v207
	v_pk_fma_f32 v[250:251], v[156:157], v[168:169], v[172:173]
	v_pk_add_f32 v[248:249], v[248:249], 1.0 op_sel_hi:[1,0]
	v_rcp_f32_e32 v248, v248
	v_rcp_f32_e32 v249, v249
	v_mov_b32_dpp v202, v136 row_shr:1 row_mask:0xf bank_mask:0xf
	v_mov_b32_dpp v203, v137 row_shr:1 row_mask:0xf bank_mask:0xf
	v_pk_fma_f32 v[250:251], v[164:165], v[194:195], v[250:251]
	v_pk_mul_f32 v[206:207], v[206:207], v[248:249]
	v_pk_fma_f32 v[202:203], v[160:161], v[202:203], v[250:251]
	v_mov_b32_dpp v200, v142 row_shr:1 row_mask:0xf bank_mask:0xf
	v_mov_b32_dpp v201, v143 row_shr:1 row_mask:0xf bank_mask:0xf
	v_pk_mul_f32 v[202:203], v[202:203], v[206:207]
	v_pk_fma_f32 v[206:207], v[154:155], v[186:187], v[190:191]
	v_mov_b32_dpp v208, v130 row_shr:1 row_mask:0xf bank_mask:0xf
	v_mov_b32_dpp v209, v131 row_shr:1 row_mask:0xf bank_mask:0xf
	v_pk_fma_f32 v[206:207], v[182:183], v[200:201], v[206:207]
	v_mov_b32_dpp v196, v150 row_shr:1 row_mask:0xf bank_mask:0xf
	v_pk_fma_f32 v[206:207], v[178:179], v[208:209], v[206:207]
	v_mov_b32_dpp v197, v151 row_shr:1 row_mask:0xf bank_mask:0xf
	v_exp_f32_e32 v193, v206
	v_exp_f32_e32 v209, v207
	v_cvt_pk_bf16_f32 v247, v202, v203
	v_add_f32_e32 v193, 1.0, v193
	v_rcp_f32_e32 v202, v193
	v_add_f32_e32 v193, 1.0, v209
	v_rcp_f32_e32 v203, v193
	v_pk_fma_f32 v[248:249], v[158:159], v[170:171], v[174:175]
	v_mov_b32_dpp v204, v138 row_shr:1 row_mask:0xf bank_mask:0xf
	v_mov_b32_dpp v205, v139 row_shr:1 row_mask:0xf bank_mask:0xf
	v_pk_fma_f32 v[248:249], v[166:167], v[196:197], v[248:249]
	v_pk_mul_f32 v[202:203], v[206:207], v[202:203]
	v_pk_fma_f32 v[204:205], v[162:163], v[204:205], v[248:249]
	v_lshl_add_u32 v246, s34, 8, v236
	v_pk_mul_f32 v[202:203], v[204:205], v[202:203]
	v_lshlrev_b64 v[204:205], 1, v[232:233]
	v_pk_fma_f32 v[232:233], v[132:133], v[184:185], v[188:189]
	v_mov_b64_e32 v[206:207], s[60:61]
	v_pk_fma_f32 v[232:233], v[152:153], v[180:181], v[232:233]
	v_cvt_pk_bf16_f32 v248, v202, v203
	v_pk_fma_f32 v[198:199], v[176:177], v[198:199], v[232:233]
	v_mad_i64_i32 v[202:203], s[34:35], v246, s74, v[206:207]
	v_exp_f32_e32 v193, v198
	v_exp_f32_e32 v232, v199
	v_lshl_add_u64 v[202:203], v[202:203], 0, v[204:205]
	v_add_f32_e32 v193, 1.0, v193
	v_rcp_f32_e32 v208, v193
	v_add_f32_e32 v193, 1.0, v232
	v_rcp_f32_e32 v209, v193
	v_pk_fma_f32 v[232:233], v[144:145], v[168:169], v[172:173]
	v_pk_fma_f32 v[140:141], v[140:141], v[184:185], v[188:189]
	v_pk_fma_f32 v[232:233], v[156:157], v[164:165], v[232:233]
	v_pk_mul_f32 v[198:199], v[198:199], v[208:209]
	v_pk_fma_f32 v[194:195], v[160:161], v[194:195], v[232:233]
	v_pk_fma_f32 v[208:209], v[146:147], v[170:171], v[174:175]
	v_pk_mul_f32 v[194:195], v[194:195], v[198:199]
	v_pk_fma_f32 v[198:199], v[134:135], v[186:187], v[190:191]
	v_pk_fma_f32 v[208:209], v[158:159], v[166:167], v[208:209]
	v_pk_fma_f32 v[198:199], v[154:155], v[182:183], v[198:199]
	v_pk_fma_f32 v[196:197], v[162:163], v[196:197], v[208:209]
	v_pk_fma_f32 v[198:199], v[178:179], v[200:201], v[198:199]
	v_cvt_pk_bf16_f32 v249, v194, v195
	v_exp_f32_e32 v200, v198
	v_exp_f32_e32 v201, v199
	v_pk_fma_f32 v[148:149], v[148:149], v[168:169], v[172:173]
	v_pk_add_f32 v[200:201], v[200:201], 1.0 op_sel_hi:[1,0]
	v_rcp_f32_e32 v200, v200
	v_rcp_f32_e32 v201, v201
	v_or_b32_e32 v193, 1, v246
	v_pk_mul_f32 v[198:199], v[198:199], v[200:201]
	s_nop 0
	v_pk_mul_f32 v[196:197], v[196:197], v[198:199]
	v_pk_fma_f32 v[198:199], v[128:129], v[184:185], v[188:189]
	v_cvt_pk_bf16_f32 v250, v196, v197
	v_pk_fma_f32 v[198:199], v[132:133], v[180:181], v[198:199]
	v_mad_i64_i32 v[196:197], s[34:35], v193, s74, v[206:207]
	v_pk_fma_f32 v[152:153], v[152:153], v[176:177], v[198:199]
	v_lshl_add_u64 v[196:197], v[196:197], 0, v[204:205]
	v_exp_f32_e32 v193, v152
	v_exp_f32_e32 v198, v153
	v_add_f32_e32 v193, 1.0, v193
	v_rcp_f32_e32 v194, v193
	v_add_f32_e32 v193, 1.0, v198
	v_rcp_f32_e32 v195, v193
	v_pk_fma_f32 v[198:199], v[136:137], v[168:169], v[172:173]
	v_pk_fma_f32 v[128:129], v[128:129], v[180:181], v[140:141]
	v_pk_fma_f32 v[198:199], v[144:145], v[164:165], v[198:199]
	v_pk_fma_f32 v[128:129], v[132:133], v[176:177], v[128:129]
	v_pk_fma_f32 v[156:157], v[156:157], v[160:161], v[198:199]
	v_pk_mul_f32 v[152:153], v[152:153], v[194:195]
	v_pk_mul_f32 v[152:153], v[156:157], v[152:153]
	v_pk_fma_f32 v[156:157], v[130:131], v[186:187], v[190:191]
	v_exp_f32_e32 v140, v128
	v_pk_fma_f32 v[132:133], v[142:143], v[186:187], v[190:191]
	v_pk_fma_f32 v[156:157], v[134:135], v[182:183], v[156:157]
	v_pk_fma_f32 v[130:131], v[130:131], v[182:183], v[132:133]
	v_pk_fma_f32 v[154:155], v[154:155], v[178:179], v[156:157]
	v_pk_fma_f32 v[130:131], v[134:135], v[178:179], v[130:131]
	v_exp_f32_e32 v157, v154
	v_exp_f32_e32 v141, v129
	v_exp_f32_e32 v132, v130
	v_exp_f32_e32 v133, v131
	v_exp_f32_e32 v193, v155
	v_pk_add_f32 v[140:141], v[140:141], 1.0 op_sel_hi:[1,0]
	v_pk_add_f32 v[132:133], v[132:133], 1.0 op_sel_hi:[1,0]
	v_cvt_pk_bf16_f32 v254, v152, v153
	v_add_f32_e32 v152, 1.0, v157
	v_add_f32_e32 v153, 1.0, v193
	v_rcp_f32_e32 v140, v140
	v_rcp_f32_e32 v141, v141
	v_rcp_f32_e32 v132, v132
; #define LAS __attribute__((address_space(3)))
; __device__ __forceinline__ float sigmoidf_(float x) { return __builtin_amdgcn_rcpf(1.0f + __expf(-x)); }
;     __device__ __forceinline__ void operator()(AccRef acc, const Unit& u, int wr, int wc, int fr, int fq) const {
;     ...
;                 f32x4 h2v = (f32x4){0.f, 0.f, 0.f, 0.f}, h3v = h2v, h2g = h2v, h3g = h2v;
;                 const int pb = ai * 2 + wr - 1;
;                 if (pb >= 0 && fr == 0) { const LAS float* xp = xch + (pb * 2) * 256 + clb + 4 * n;
;                     h2v = *(const LAS f32x4*)(xp); h3v = *(const LAS f32x4*)(xp + 256); h2g = *(const LAS f32x4*)(xp + 128); h3g = *(const LAS f32x4*)(xp + 256 + 128); }
;                 float o[4][4];
; #pragma unroll
;                 for (int j = 0; j < 4; ++j) {
;                     const float v0 = acc[ai][0][0][n][j], v1 = acc[ai][0][1][n][j], v2 = acc[ai][0][2][n][j], v3 = acc[ai][0][3][n][j];
;                     const float g0 = acc[ai][1][0][n][j], g1 = acc[ai][1][1][n][j], g2 = acc[ai][1][2][n][j], g3 = acc[ai][1][3][n][j];
;                     const float pv3 = dpp_upd<0x111>(h3v[j], v3), pv2 = dpp_upd<0x111>(h2v[j], v2), pg3 = dpp_upd<0x111>(h3g[j], g3), pg2 = dpp_upd<0x111>(h2g[j], g2);
;                     const float hv0 = bvv[j] + w2v[j] * v0 + w1v[j] * pv3 + w0v[j] * pv2, hv1 = bvv[j] + w2v[j] * v1 + w1v[j] * v0 + w0v[j] * pv3;
;                     const float hv2 = bvv[j] + w2v[j] * v2 + w1v[j] * v1 + w0v[j] * v0, hv3 = bvv[j] + w2v[j] * v3 + w1v[j] * v2 + w0v[j] * v1;
;                     const float hg0 = bvg[j] + w2g[j] * g0 + w1g[j] * pg3 + w0g[j] * pg2, hg1 = bvg[j] + w2g[j] * g1 + w1g[j] * g0 + w0g[j] * pg3;
;                     const float hg2 = bvg[j] + w2g[j] * g2 + w1g[j] * g1 + w0g[j] * g0, hg3 = bvg[j] + w2g[j] * g3 + w1g[j] * g2 + w0g[j] * g1;
;                     o[0][j] = hg0 * sigmoidf_(hg0) * hv0; o[1][j] = hg1 * sigmoidf_(hg1) * hv1; o[2][j] = hg2 * sigmoidf_(hg2) * hv2; o[3][j] = hg3 * sigmoidf_(hg3) * hv3; }
; #pragma unroll
;                 for (int m = 0; m < 4; ++m) { u32x2 w; w.x = cvt_pk_bf16(o[m][0], o[m][1]); w.y = cvt_pk_bf16(o[m][2], o[m][3]);
;                     *(u32x2*)(Aout + (size_t)(row0 + ai * 128 + m) * FH + hc0 + 4 * n) = w; } } }
	v_rcp_f32_e32 v133, v133
	v_rcp_f32_e32 v152, v152
	v_rcp_f32_e32 v153, v153
	v_pk_fma_f32 v[142:143], v[150:151], v[170:171], v[174:175]
	v_pk_fma_f32 v[194:195], v[138:139], v[170:171], v[174:175]
	v_pk_fma_f32 v[136:137], v[136:137], v[164:165], v[148:149]
	v_pk_fma_f32 v[134:135], v[138:139], v[166:167], v[142:143]
	v_pk_fma_f32 v[194:195], v[146:147], v[166:167], v[194:195]
	v_pk_fma_f32 v[136:137], v[144:145], v[160:161], v[136:137]
	v_pk_mul_f32 v[128:129], v[128:129], v[140:141]
	v_pk_fma_f32 v[134:135], v[146:147], v[162:163], v[134:135]
	v_pk_mul_f32 v[130:131], v[130:131], v[132:133]
	v_pk_fma_f32 v[158:159], v[158:159], v[162:163], v[194:195]
	v_pk_mul_f32 v[152:153], v[154:155], v[152:153]
	v_pk_mul_f32 v[128:129], v[136:137], v[128:129]
	v_pk_mul_f32 v[130:131], v[134:135], v[130:131]
	v_pk_mul_f32 v[152:153], v[158:159], v[152:153]
	v_cvt_pk_bf16_f32 v251, v128, v129
	v_cvt_pk_bf16_f32 v253, v130, v131
	v_or_b32_e32 v130, 3, v246
	v_cvt_pk_bf16_f32 v255, v152, v153
	v_or_b32_e32 v152, 2, v246
	v_mad_i64_i32 v[130:131], s[34:35], v130, s74, v[206:207]
	v_mad_i64_i32 v[152:153], s[34:35], v152, s74, v[206:207]
	v_lshl_add_u64 v[140:141], v[130:131], 0, v[204:205]
	v_lshl_add_u64 v[152:153], v[152:153], 0, v[204:205]
	v_mov_b32_e32 v193, 0
	v_mov_b64_e32 v[194:195], 0
	v_mov_b64_e32 v[136:137], 0
	v_mov_b64_e32 v[138:139], 0
	v_mov_b64_e32 v[128:129], 0
	v_mov_b64_e32 v[130:131], 0
	v_mov_b64_e32 v[132:133], 0
	v_mov_b64_e32 v[134:135], 0
	s_barrier
	s_and_saveexec_b64 s[34:35], s[22:23]
	s_cbranch_execz .LBB0_320
	ds_read_b128 v[132:135], v237 offset:2048
	ds_read_b128 v[136:139], v237 offset:2560
	ds_read_b128 v[128:131], v237 offset:3072
	ds_read_b128 v[192:195], v237 offset:3584
.LBB0_320:
	s_or_b64 exec, exec, s[34:35]
	s_waitcnt lgkmcnt(0)
	v_mov_b32_dpp v192, v72 row_shr:1 row_mask:0xf bank_mask:0xf
	v_mov_b32_dpp v193, v73 row_shr:1 row_mask:0xf bank_mask:0xf
	v_pk_fma_f32 v[142:143], v[88:89], v[184:185], v[188:189]
	v_mov_b32_dpp v136, v64 row_shr:1 row_mask:0xf bank_mask:0xf
	v_mov_b32_dpp v137, v65 row_shr:1 row_mask:0xf bank_mask:0xf
	v_pk_fma_f32 v[142:143], v[180:181], v[192:193], v[142:143]
	v_mov_b32_dpp v128, v84 row_shr:1 row_mask:0xf bank_mask:0xf
	v_pk_fma_f32 v[136:137], v[176:177], v[136:137], v[142:143]
	v_mov_b32_dpp v129, v85 row_shr:1 row_mask:0xf bank_mask:0xf
	v_exp_f32_e32 v142, v136
	v_exp_f32_e32 v143, v137
	v_pk_fma_f32 v[144:145], v[92:93], v[168:169], v[172:173]
	v_mov_b32_dpp v132, v76 row_shr:1 row_mask:0xf bank_mask:0xf
	v_pk_add_f32 v[142:143], v[142:143], 1.0 op_sel_hi:[1,0]
	v_rcp_f32_e32 v142, v142
	v_rcp_f32_e32 v143, v143
	v_mov_b32_dpp v133, v77 row_shr:1 row_mask:0xf bank_mask:0xf
	v_pk_fma_f32 v[144:145], v[164:165], v[128:129], v[144:145]
	v_mov_b32_dpp v194, v74 row_shr:1 row_mask:0xf bank_mask:0xf
	v_pk_fma_f32 v[132:133], v[160:161], v[132:133], v[144:145]
	v_pk_mul_f32 v[136:137], v[136:137], v[142:143]
	v_mov_b32_dpp v195, v75 row_shr:1 row_mask:0xf bank_mask:0xf
	v_pk_mul_f32 v[132:133], v[132:133], v[136:137]
	v_pk_fma_f32 v[136:137], v[90:91], v[186:187], v[190:191]
	v_mov_b32_dpp v138, v66 row_shr:1 row_mask:0xf bank_mask:0xf
	v_mov_b32_dpp v139, v67 row_shr:1 row_mask:0xf bank_mask:0xf
	v_pk_fma_f32 v[136:137], v[182:183], v[194:195], v[136:137]
	v_mov_b32_dpp v130, v86 row_shr:1 row_mask:0xf bank_mask:0xf
	v_pk_fma_f32 v[136:137], v[178:179], v[138:139], v[136:137]
	v_mov_b32_dpp v131, v87 row_shr:1 row_mask:0xf bank_mask:0xf
	v_exp_f32_e32 v139, v136
	v_exp_f32_e32 v142, v137
	v_cvt_pk_bf16_f32 v144, v132, v133
	v_add_f32_e32 v132, 1.0, v139
	v_rcp_f32_e32 v132, v132
	v_add_f32_e32 v133, 1.0, v142
	v_rcp_f32_e32 v133, v133
	v_pk_fma_f32 v[142:143], v[94:95], v[170:171], v[174:175]
	v_mov_b32_dpp v134, v78 row_shr:1 row_mask:0xf bank_mask:0xf
	v_mov_b32_dpp v135, v79 row_shr:1 row_mask:0xf bank_mask:0xf
	v_pk_mul_f32 v[132:133], v[136:137], v[132:133]
	v_pk_fma_f32 v[136:137], v[68:69], v[184:185], v[188:189]
	v_pk_fma_f32 v[142:143], v[166:167], v[130:131], v[142:143]
	v_pk_fma_f32 v[136:137], v[88:89], v[180:181], v[136:137]
	v_pk_fma_f32 v[134:135], v[162:163], v[134:135], v[142:143]
	v_pk_fma_f32 v[136:137], v[176:177], v[192:193], v[136:137]
	v_add_u32_e32 v146, 0x80, v246
	v_exp_f32_e32 v142, v136
	v_exp_f32_e32 v143, v137
	v_pk_mul_f32 v[132:133], v[134:135], v[132:133]
	v_mov_b64_e32 v[134:135], s[60:61]
	v_cvt_pk_bf16_f32 v145, v132, v133
	v_mad_i64_i32 v[132:133], s[34:35], v146, s74, v[134:135]
	v_lshl_add_u64 v[132:133], v[132:133], 0, v[204:205]
	v_add_f32_e32 v138, 1.0, v142
	v_add_f32_e32 v139, 1.0, v143
	v_rcp_f32_e32 v138, v138
	v_rcp_f32_e32 v139, v139
	v_pk_fma_f32 v[142:143], v[80:81], v[168:169], v[172:173]
	v_pk_fma_f32 v[72:73], v[72:73], v[184:185], v[188:189]
	v_pk_fma_f32 v[142:143], v[92:93], v[164:165], v[142:143]
	v_pk_mul_f32 v[136:137], v[136:137], v[138:139]
	v_pk_fma_f32 v[128:129], v[160:161], v[128:129], v[142:143]
	v_pk_fma_f32 v[84:85], v[84:85], v[168:169], v[172:173]
	v_pk_mul_f32 v[128:129], v[128:129], v[136:137]
	v_pk_fma_f32 v[136:137], v[70:71], v[186:187], v[190:191]
	s_nop 0
	v_pk_fma_f32 v[136:137], v[90:91], v[182:183], v[136:137]
	s_nop 0
	v_pk_fma_f32 v[136:137], v[178:179], v[194:195], v[136:137]
	s_nop 0
	v_exp_f32_e32 v139, v136
	v_exp_f32_e32 v142, v137
	v_cvt_pk_bf16_f32 v138, v128, v129
	v_add_f32_e32 v128, 1.0, v139
	v_rcp_f32_e32 v128, v128
	v_add_f32_e32 v129, 1.0, v142
	v_rcp_f32_e32 v129, v129
	v_pk_fma_f32 v[142:143], v[82:83], v[170:171], v[174:175]
	v_pk_mul_f32 v[128:129], v[136:137], v[128:129]
	v_pk_fma_f32 v[142:143], v[94:95], v[166:167], v[142:143]
	v_pk_fma_f32 v[136:137], v[76:77], v[168:169], v[172:173]
; #define LAS __attribute__((address_space(3)))
; __device__ __forceinline__ float sigmoidf_(float x) { return __builtin_amdgcn_rcpf(1.0f + __expf(-x)); }
;     __device__ __forceinline__ void operator()(AccRef acc, const Unit& u, int wr, int wc, int fr, int fq) const {
;     ...
;                 f32x4 h2v = (f32x4){0.f, 0.f, 0.f, 0.f}, h3v = h2v, h2g = h2v, h3g = h2v;
;                 const int pb = ai * 2 + wr - 1;
;                 if (pb >= 0 && fr == 0) { const LAS float* xp = xch + (pb * 2) * 256 + clb + 4 * n;
;                     h2v = *(const LAS f32x4*)(xp); h3v = *(const LAS f32x4*)(xp + 256); h2g = *(const LAS f32x4*)(xp + 128); h3g = *(const LAS f32x4*)(xp + 256 + 128); }
;                 float o[4][4];
; #pragma unroll
;                 for (int j = 0; j < 4; ++j) {
;                     const float v0 = acc[ai][0][0][n][j], v1 = acc[ai][0][1][n][j], v2 = acc[ai][0][2][n][j], v3 = acc[ai][0][3][n][j];
;                     const float g0 = acc[ai][1][0][n][j], g1 = acc[ai][1][1][n][j], g2 = acc[ai][1][2][n][j], g3 = acc[ai][1][3][n][j];
;                     const float pv3 = dpp_upd<0x111>(h3v[j], v3), pv2 = dpp_upd<0x111>(h2v[j], v2), pg3 = dpp_upd<0x111>(h3g[j], g3), pg2 = dpp_upd<0x111>(h2g[j], g2);
;                     const float hv0 = bvv[j] + w2v[j] * v0 + w1v[j] * pv3 + w0v[j] * pv2, hv1 = bvv[j] + w2v[j] * v1 + w1v[j] * v0 + w0v[j] * pv3;
;                     const float hv2 = bvv[j] + w2v[j] * v2 + w1v[j] * v1 + w0v[j] * v0, hv3 = bvv[j] + w2v[j] * v3 + w1v[j] * v2 + w0v[j] * v1;
;                     const float hg0 = bvg[j] + w2g[j] * g0 + w1g[j] * pg3 + w0g[j] * pg2, hg1 = bvg[j] + w2g[j] * g1 + w1g[j] * g0 + w0g[j] * pg3;
;                     const float hg2 = bvg[j] + w2g[j] * g2 + w1g[j] * g1 + w0g[j] * g0, hg3 = bvg[j] + w2g[j] * g3 + w1g[j] * g2 + w0g[j] * g1;
;                     o[0][j] = hg0 * sigmoidf_(hg0) * hv0; o[1][j] = hg1 * sigmoidf_(hg1) * hv1; o[2][j] = hg2 * sigmoidf_(hg2) * hv2; o[3][j] = hg3 * sigmoidf_(hg3) * hv3; }
; #pragma unroll
;                 for (int m = 0; m < 4; ++m) { u32x2 w; w.x = cvt_pk_bf16(o[m][0], o[m][1]); w.y = cvt_pk_bf16(o[m][2], o[m][3]);
;                     *(u32x2*)(Aout + (size_t)(row0 + ai * 128 + m) * FH + hc0 + 4 * n) = w; } } }
	v_pk_fma_f32 v[130:131], v[162:163], v[130:131], v[142:143]
	v_pk_fma_f32 v[136:137], v[80:81], v[164:165], v[136:137]
	v_pk_mul_f32 v[128:129], v[130:131], v[128:129]
	v_pk_fma_f32 v[130:131], v[64:65], v[184:185], v[188:189]
	v_pk_fma_f32 v[64:65], v[64:65], v[180:181], v[72:73]
	v_pk_fma_f32 v[130:131], v[68:69], v[180:181], v[130:131]
	v_pk_fma_f32 v[64:65], v[68:69], v[176:177], v[64:65]
	v_pk_fma_f32 v[88:89], v[88:89], v[176:177], v[130:131]
	v_pk_fma_f32 v[92:93], v[92:93], v[160:161], v[136:137]
	v_exp_f32_e32 v130, v88
	v_exp_f32_e32 v131, v89
	v_exp_f32_e32 v72, v64
	v_pk_add_f32 v[130:131], v[130:131], 1.0 op_sel_hi:[1,0]
	v_rcp_f32_e32 v130, v130
	v_rcp_f32_e32 v131, v131
	v_pk_fma_f32 v[68:69], v[74:75], v[186:187], v[190:191]
	v_exp_f32_e32 v73, v65
	v_pk_mul_f32 v[88:89], v[88:89], v[130:131]
	v_pk_mul_f32 v[88:89], v[92:93], v[88:89]
	v_pk_fma_f32 v[92:93], v[66:67], v[186:187], v[190:191]
	v_pk_fma_f32 v[66:67], v[66:67], v[182:183], v[68:69]
	v_pk_fma_f32 v[92:93], v[70:71], v[182:183], v[92:93]
	v_pk_fma_f32 v[66:67], v[70:71], v[178:179], v[66:67]
	v_pk_fma_f32 v[90:91], v[90:91], v[178:179], v[92:93]
	v_exp_f32_e32 v93, v90
	v_exp_f32_e32 v68, v66
	v_exp_f32_e32 v69, v67
	v_exp_f32_e32 v130, v91
	v_pk_add_f32 v[72:73], v[72:73], 1.0 op_sel_hi:[1,0]
	v_pk_add_f32 v[68:69], v[68:69], 1.0 op_sel_hi:[1,0]
	v_cvt_pk_bf16_f32 v198, v88, v89
	v_add_f32_e32 v88, 1.0, v93
	v_add_f32_e32 v89, 1.0, v130
	v_rcp_f32_e32 v72, v72
	v_rcp_f32_e32 v73, v73
	v_rcp_f32_e32 v68, v68
	v_rcp_f32_e32 v69, v69
	v_rcp_f32_e32 v88, v88
	v_rcp_f32_e32 v89, v89
	v_pk_fma_f32 v[74:75], v[86:87], v[170:171], v[174:175]
	v_pk_fma_f32 v[130:131], v[78:79], v[170:171], v[174:175]
	v_pk_fma_f32 v[76:77], v[76:77], v[164:165], v[84:85]
	v_pk_fma_f32 v[70:71], v[78:79], v[166:167], v[74:75]
	v_pk_fma_f32 v[130:131], v[82:83], v[166:167], v[130:131]
	v_pk_fma_f32 v[76:77], v[80:81], v[160:161], v[76:77]
	v_pk_mul_f32 v[64:65], v[64:65], v[72:73]
	v_pk_fma_f32 v[70:71], v[82:83], v[162:163], v[70:71]
	v_pk_mul_f32 v[66:67], v[66:67], v[68:69]
	v_pk_fma_f32 v[94:95], v[94:95], v[162:163], v[130:131]
	v_pk_mul_f32 v[88:89], v[90:91], v[88:89]
	v_pk_mul_f32 v[64:65], v[76:77], v[64:65]
	v_pk_mul_f32 v[66:67], v[70:71], v[66:67]
	v_pk_mul_f32 v[88:89], v[94:95], v[88:89]
	v_cvt_pk_bf16_f32 v148, v64, v65
	v_cvt_pk_bf16_f32 v149, v66, v67
	v_add_u32_e32 v66, 0x83, v246
	v_cvt_pk_bf16_f32 v155, v128, v129
	v_add_u32_e32 v128, 0x81, v246
	v_cvt_pk_bf16_f32 v199, v88, v89
	v_add_u32_e32 v88, 0x82, v246
	v_mad_i64_i32 v[66:67], s[34:35], v66, s74, v[134:135]
	v_mad_i64_i32 v[128:129], s[34:35], v128, s74, v[134:135]
	v_mad_i64_i32 v[88:89], s[34:35], v88, s74, v[134:135]
	v_lshl_add_u64 v[82:83], v[66:67], 0, v[204:205]
	v_lshl_add_u64 v[128:129], v[128:129], 0, v[204:205]
	v_lshl_add_u64 v[88:89], v[88:89], 0, v[204:205]
	v_mov_b32_e32 v64, 0
	v_mov_b64_e32 v[70:71], 0
	v_mov_b64_e32 v[72:73], 0
	v_mov_b64_e32 v[78:79], 0
	v_mov_b64_e32 v[80:81], 0
	v_mov_b64_e32 v[66:67], 0
	v_mov_b64_e32 v[68:69], 0
	v_mov_b64_e32 v[74:75], 0
	v_mov_b64_e32 v[76:77], 0
	v_mov_b32_e32 v154, v138
	s_barrier
	s_and_saveexec_b64 s[34:35], s[18:19]
	s_cbranch_execz .LBB0_322
	ds_read_b128 v[74:77], v242
	ds_read_b128 v[66:69], v241
	ds_read_b128 v[78:81], v240
	ds_read_b128 v[70:73], v239
; #define LAS __attribute__((address_space(3)))
; __device__ __forceinline__ float sigmoidf_(float x) { return __builtin_amdgcn_rcpf(1.0f + __expf(-x)); }
;     __device__ __forceinline__ void operator()(AccRef acc, const Unit& u, int wr, int wc, int fr, int fq) const {
;     ...
;                 f32x4 h2v = (f32x4){0.f, 0.f, 0.f, 0.f}, h3v = h2v, h2g = h2v, h3g = h2v;
;                 const int pb = ai * 2 + wr - 1;
;                 if (pb >= 0 && fr == 0) { const LAS float* xp = xch + (pb * 2) * 256 + clb + 4 * n;
;                     h2v = *(const LAS f32x4*)(xp); h3v = *(const LAS f32x4*)(xp + 256); h2g = *(const LAS f32x4*)(xp + 128); h3g = *(const LAS f32x4*)(xp + 256 + 128); }
;                 float o[4][4];
; #pragma unroll
;                 for (int j = 0; j < 4; ++j) {
;                     const float v0 = acc[ai][0][0][n][j], v1 = acc[ai][0][1][n][j], v2 = acc[ai][0][2][n][j], v3 = acc[ai][0][3][n][j];
;                     const float g0 = acc[ai][1][0][n][j], g1 = acc[ai][1][1][n][j], g2 = acc[ai][1][2][n][j], g3 = acc[ai][1][3][n][j];
;                     const float pv3 = dpp_upd<0x111>(h3v[j], v3), pv2 = dpp_upd<0x111>(h2v[j], v2), pg3 = dpp_upd<0x111>(h3g[j], g3), pg2 = dpp_upd<0x111>(h2g[j], g2);
;                     const float hv0 = bvv[j] + w2v[j] * v0 + w1v[j] * pv3 + w0v[j] * pv2, hv1 = bvv[j] + w2v[j] * v1 + w1v[j] * v0 + w0v[j] * pv3;
;                     const float hv2 = bvv[j] + w2v[j] * v2 + w1v[j] * v1 + w0v[j] * v0, hv3 = bvv[j] + w2v[j] * v3 + w1v[j] * v2 + w0v[j] * v1;
;                     const float hg0 = bvg[j] + w2g[j] * g0 + w1g[j] * pg3 + w0g[j] * pg2, hg1 = bvg[j] + w2g[j] * g1 + w1g[j] * g0 + w0g[j] * pg3;
;                     const float hg2 = bvg[j] + w2g[j] * g2 + w1g[j] * g1 + w0g[j] * g0, hg3 = bvg[j] + w2g[j] * g3 + w1g[j] * g2 + w0g[j] * g1;
;                     o[0][j] = hg0 * sigmoidf_(hg0) * hv0; o[1][j] = hg1 * sigmoidf_(hg1) * hv1; o[2][j] = hg2 * sigmoidf_(hg2) * hv2; o[3][j] = hg3 * sigmoidf_(hg3) * hv3; }
; #pragma unroll
;                 for (int m = 0; m < 4; ++m) { u32x2 w; w.x = cvt_pk_bf16(o[m][0], o[m][1]); w.y = cvt_pk_bf16(o[m][2], o[m][3]);
;                     *(u32x2*)(Aout + (size_t)(row0 + ai * 128 + m) * FH + hc0 + 4 * n) = w; } } }
.LBB0_322:
	s_or_b64 exec, exec, s[34:35]
	s_waitcnt lgkmcnt(0)
	v_mov_b32_dpp v70, v44 row_shr:1 row_mask:0xf bank_mask:0xf
	v_mov_b32_dpp v71, v45 row_shr:1 row_mask:0xf bank_mask:0xf
	s_waitcnt vmcnt(0)
	v_pk_fma_f32 v[84:85], v[56:57], v[120:121], v[124:125]
	v_mov_b32_dpp v78, v32 row_shr:1 row_mask:0xf bank_mask:0xf
	v_mov_b32_dpp v79, v33 row_shr:1 row_mask:0xf bank_mask:0xf
	v_pk_fma_f32 v[84:85], v[116:117], v[70:71], v[84:85]
	v_mov_b32_dpp v66, v52 row_shr:1 row_mask:0xf bank_mask:0xf
	v_pk_fma_f32 v[78:79], v[112:113], v[78:79], v[84:85]
	v_mov_b32_dpp v67, v53 row_shr:1 row_mask:0xf bank_mask:0xf
	v_exp_f32_e32 v84, v78
	v_exp_f32_e32 v85, v79
	v_pk_fma_f32 v[86:87], v[60:61], v[104:105], v[108:109]
	v_pk_add_f32 v[84:85], v[84:85], 1.0 op_sel_hi:[1,0]
	v_rcp_f32_e32 v84, v84
	v_rcp_f32_e32 v85, v85
	v_mov_b32_dpp v74, v40 row_shr:1 row_mask:0xf bank_mask:0xf
	v_mov_b32_dpp v75, v41 row_shr:1 row_mask:0xf bank_mask:0xf
	v_pk_fma_f32 v[86:87], v[100:101], v[66:67], v[86:87]
	v_pk_mul_f32 v[78:79], v[78:79], v[84:85]
	v_pk_fma_f32 v[74:75], v[96:97], v[74:75], v[86:87]
	v_mov_b32_dpp v72, v46 row_shr:1 row_mask:0xf bank_mask:0xf
	v_mov_b32_dpp v73, v47 row_shr:1 row_mask:0xf bank_mask:0xf
	v_pk_mul_f32 v[74:75], v[74:75], v[78:79]
	v_pk_fma_f32 v[78:79], v[58:59], v[122:123], v[126:127]
	v_mov_b32_dpp v80, v34 row_shr:1 row_mask:0xf bank_mask:0xf
	v_mov_b32_dpp v81, v35 row_shr:1 row_mask:0xf bank_mask:0xf
	v_pk_fma_f32 v[78:79], v[118:119], v[72:73], v[78:79]
	v_mov_b32_dpp v68, v54 row_shr:1 row_mask:0xf bank_mask:0xf
	v_pk_fma_f32 v[78:79], v[114:115], v[80:81], v[78:79]
	v_mov_b32_dpp v69, v55 row_shr:1 row_mask:0xf bank_mask:0xf
	v_exp_f32_e32 v80, v78
	v_exp_f32_e32 v81, v79
	v_pk_fma_f32 v[84:85], v[62:63], v[106:107], v[110:111]
	v_pk_add_f32 v[80:81], v[80:81], 1.0 op_sel_hi:[1,0]
	v_rcp_f32_e32 v80, v80
	v_rcp_f32_e32 v81, v81
	v_mov_b32_dpp v76, v42 row_shr:1 row_mask:0xf bank_mask:0xf
	v_mov_b32_dpp v77, v43 row_shr:1 row_mask:0xf bank_mask:0xf
	v_pk_fma_f32 v[84:85], v[102:103], v[68:69], v[84:85]
	v_pk_mul_f32 v[78:79], v[78:79], v[80:81]
	v_pk_fma_f32 v[76:77], v[98:99], v[76:77], v[84:85]
	v_cvt_pk_bf16_f32 v92, v74, v75
	v_pk_mul_f32 v[76:77], v[76:77], v[78:79]
	v_pk_fma_f32 v[44:45], v[44:45], v[120:121], v[124:125]
	v_cvt_pk_bf16_f32 v93, v76, v77
	v_pk_fma_f32 v[76:77], v[36:37], v[120:121], v[124:125]
	v_mov_b32_e32 v90, v247
	v_mov_b32_e32 v91, v248
	global_store_dwordx4 v[202:203], v[90:93], off
	v_pk_fma_f32 v[76:77], v[56:57], v[116:117], v[76:77]
	v_pk_fma_f32 v[52:53], v[52:53], v[104:105], v[108:109]
	v_pk_fma_f32 v[70:71], v[112:113], v[70:71], v[76:77]
	s_nop 0
	v_exp_f32_e32 v74, v70
	v_exp_f32_e32 v75, v71
	s_nop 0
	v_pk_add_f32 v[74:75], v[74:75], 1.0 op_sel_hi:[1,0]
	v_rcp_f32_e32 v74, v74
	v_rcp_f32_e32 v75, v75
	v_pk_fma_f32 v[76:77], v[48:49], v[104:105], v[108:109]
	v_pk_mul_f32 v[70:71], v[70:71], v[74:75]
	v_pk_fma_f32 v[76:77], v[60:61], v[100:101], v[76:77]
	v_pk_fma_f32 v[74:75], v[50:51], v[106:107], v[110:111]
	v_pk_fma_f32 v[66:67], v[96:97], v[66:67], v[76:77]
	v_pk_fma_f32 v[74:75], v[62:63], v[102:103], v[74:75]
	v_pk_mul_f32 v[66:67], v[66:67], v[70:71]
	v_pk_fma_f32 v[70:71], v[38:39], v[122:123], v[126:127]
	v_pk_fma_f32 v[68:69], v[98:99], v[68:69], v[74:75]
	v_pk_fma_f32 v[70:71], v[58:59], v[118:119], v[70:71]
	v_cvt_pk_bf16_f32 v136, v66, v67
	v_pk_fma_f32 v[70:71], v[114:115], v[72:73], v[70:71]
	s_nop 0
	v_exp_f32_e32 v72, v70
	v_exp_f32_e32 v73, v71
	s_nop 0
	v_pk_add_f32 v[72:73], v[72:73], 1.0 op_sel_hi:[1,0]
	v_rcp_f32_e32 v72, v72
	v_rcp_f32_e32 v73, v73
	s_nop 0
	v_pk_mul_f32 v[70:71], v[70:71], v[72:73]
	s_nop 0
	v_pk_mul_f32 v[68:69], v[68:69], v[70:71]
	s_nop 0
	v_cvt_pk_bf16_f32 v137, v68, v69
	v_pk_fma_f32 v[68:69], v[32:33], v[120:121], v[124:125]
	v_mov_b32_e32 v134, v249
	v_mov_b32_e32 v135, v250
	global_store_dwordx4 v[196:197], v[134:137], off
	v_pk_fma_f32 v[68:69], v[36:37], v[116:117], v[68:69]
	v_pk_fma_f32 v[32:33], v[32:33], v[116:117], v[44:45]
	v_pk_fma_f32 v[56:57], v[56:57], v[112:113], v[68:69]
	v_pk_fma_f32 v[32:33], v[36:37], v[112:113], v[32:33]
	v_exp_f32_e32 v66, v56
	v_exp_f32_e32 v67, v57
	s_nop 0
	v_pk_add_f32 v[66:67], v[66:67], 1.0 op_sel_hi:[1,0]
	v_rcp_f32_e32 v66, v66
	v_rcp_f32_e32 v67, v67
	v_pk_fma_f32 v[68:69], v[40:41], v[104:105], v[108:109]
	v_exp_f32_e32 v44, v32
	v_pk_fma_f32 v[68:69], v[48:49], v[100:101], v[68:69]
	v_pk_mul_f32 v[56:57], v[56:57], v[66:67]
	v_pk_fma_f32 v[60:61], v[60:61], v[96:97], v[68:69]
	v_pk_fma_f32 v[36:37], v[46:47], v[122:123], v[126:127]
	v_pk_mul_f32 v[56:57], v[60:61], v[56:57]
	v_pk_fma_f32 v[60:61], v[34:35], v[122:123], v[126:127]
	v_pk_fma_f32 v[34:35], v[34:35], v[118:119], v[36:37]
	v_pk_fma_f32 v[60:61], v[38:39], v[118:119], v[60:61]
	v_pk_fma_f32 v[34:35], v[38:39], v[114:115], v[34:35]
	v_pk_fma_f32 v[58:59], v[58:59], v[114:115], v[60:61]
	v_exp_f32_e32 v60, v58
	v_exp_f32_e32 v45, v33
	v_exp_f32_e32 v36, v34
	v_exp_f32_e32 v37, v35
	v_exp_f32_e32 v61, v59
	v_cvt_pk_bf16_f32 v164, v56, v57
	v_pk_add_f32 v[44:45], v[44:45], 1.0 op_sel_hi:[1,0]
	v_pk_add_f32 v[36:37], v[36:37], 1.0 op_sel_hi:[1,0]
	v_pk_add_f32 v[60:61], v[60:61], 1.0 op_sel_hi:[1,0]
	v_rcp_f32_e32 v44, v44
	v_rcp_f32_e32 v45, v45
	v_rcp_f32_e32 v36, v36
	v_rcp_f32_e32 v37, v37
	v_rcp_f32_e32 v60, v60
	v_rcp_f32_e32 v61, v61
	v_pk_fma_f32 v[46:47], v[54:55], v[106:107], v[110:111]
	v_pk_fma_f32 v[66:67], v[42:43], v[106:107], v[110:111]
	v_pk_fma_f32 v[40:41], v[40:41], v[100:101], v[52:53]
	v_pk_fma_f32 v[38:39], v[42:43], v[102:103], v[46:47]
	v_pk_fma_f32 v[66:67], v[50:51], v[102:103], v[66:67]
	v_pk_fma_f32 v[40:41], v[48:49], v[96:97], v[40:41]
	v_pk_mul_f32 v[32:33], v[32:33], v[44:45]
	v_pk_fma_f32 v[38:39], v[50:51], v[98:99], v[38:39]
	v_pk_mul_f32 v[34:35], v[34:35], v[36:37]
	v_pk_fma_f32 v[62:63], v[62:63], v[98:99], v[66:67]
	v_pk_mul_f32 v[58:59], v[58:59], v[60:61]
	v_pk_mul_f32 v[32:33], v[40:41], v[32:33]
	v_pk_mul_f32 v[34:35], v[38:39], v[34:35]
	v_pk_mul_f32 v[58:59], v[62:63], v[58:59]
	v_cvt_pk_bf16_f32 v160, v32, v33
	v_cvt_pk_bf16_f32 v161, v34, v35
	v_cvt_pk_bf16_f32 v57, v58, v59
	v_mov_b32_e32 v158, v251
	v_mov_b32_e32 v159, v253
	global_store_dwordx4 v[140:141], v[158:161], off
	v_mov_b32_e32 v65, 0
	v_mov_b64_e32 v[66:67], 0
	v_mov_b64_e32 v[40:41], 0
	v_mov_b64_e32 v[42:43], 0
	v_mov_b64_e32 v[32:33], 0
	v_mov_b64_e32 v[34:35], 0
	v_mov_b64_e32 v[36:37], 0
	v_mov_b64_e32 v[38:39], 0
	v_mov_b32_e32 v162, v254
	v_mov_b32_e32 v163, v255
	v_mov_b32_e32 v165, v57
	global_store_dwordx4 v[152:153], v[162:165], off
	s_barrier
	s_and_saveexec_b64 s[34:35], s[22:23]
	s_cbranch_execz .LBB0_305
	ds_read_b128 v[36:39], v237 offset:2064
	ds_read_b128 v[40:43], v237 offset:2576
	ds_read_b128 v[32:35], v237 offset:3088
	ds_read_b128 v[64:67], v237 offset:3600
	s_branch .LBB0_305

; #define LAS __attribute__((address_space(3)))
; __device__ __forceinline__ float sigmoidf_(float x) { return __builtin_amdgcn_rcpf(1.0f + __expf(-x)); }
;     __device__ __forceinline__ void operator()(AccRef acc, const Unit& u, int wr, int wc, int fr, int fq) const {
;     ...
;                 f32x4 h2v = (f32x4){0.f, 0.f, 0.f, 0.f}, h3v = h2v, h2g = h2v, h3g = h2v;
;                 const int pb = ai * 2 + wr - 1;
;                 if (pb >= 0 && fr == 0) { const LAS float* xp = xch + (pb * 2) * 256 + clb + 4 * n;
;                     h2v = *(const LAS f32x4*)(xp); h3v = *(const LAS f32x4*)(xp + 256); h2g = *(const LAS f32x4*)(xp + 128); h3g = *(const LAS f32x4*)(xp + 256 + 128); }
;                 float o[4][4];
; #pragma unroll
;                 for (int j = 0; j < 4; ++j) {
;                     const float v0 = acc[ai][0][0][n][j], v1 = acc[ai][0][1][n][j], v2 = acc[ai][0][2][n][j], v3 = acc[ai][0][3][n][j];
;                     const float g0 = acc[ai][1][0][n][j], g1 = acc[ai][1][1][n][j], g2 = acc[ai][1][2][n][j], g3 = acc[ai][1][3][n][j];
;                     const float pv3 = dpp_upd<0x111>(h3v[j], v3), pv2 = dpp_upd<0x111>(h2v[j], v2), pg3 = dpp_upd<0x111>(h3g[j], g3), pg2 = dpp_upd<0x111>(h2g[j], g2);
;                     const float hv0 = bvv[j] + w2v[j] * v0 + w1v[j] * pv3 + w0v[j] * pv2, hv1 = bvv[j] + w2v[j] * v1 + w1v[j] * v0 + w0v[j] * pv3;
;                     const float hv2 = bvv[j] + w2v[j] * v2 + w1v[j] * v1 + w0v[j] * v0, hv3 = bvv[j] + w2v[j] * v3 + w1v[j] * v2 + w0v[j] * v1;
;                     const float hg0 = bvg[j] + w2g[j] * g0 + w1g[j] * pg3 + w0g[j] * pg2, hg1 = bvg[j] + w2g[j] * g1 + w1g[j] * g0 + w0g[j] * pg3;
;                     const float hg2 = bvg[j] + w2g[j] * g2 + w1g[j] * g1 + w0g[j] * g0, hg3 = bvg[j] + w2g[j] * g3 + w1g[j] * g2 + w0g[j] * g1;
;                     o[0][j] = hg0 * sigmoidf_(hg0) * hv0; o[1][j] = hg1 * sigmoidf_(hg1) * hv1; o[2][j] = hg2 * sigmoidf_(hg2) * hv2; o[3][j] = hg3 * sigmoidf_(hg3) * hv3; }
; #pragma unroll
;                 for (int m = 0; m < 4; ++m) { u32x2 w; w.x = cvt_pk_bf16(o[m][0], o[m][1]); w.y = cvt_pk_bf16(o[m][2], o[m][3]);
;                     *(u32x2*)(Aout + (size_t)(row0 + ai * 128 + m) * FH + hc0 + 4 * n) = w; } } }
.LBB0_765:
	s_or_b64 exec, exec, s[46:47]
	v_pk_fma_f32 v[248:249], v[152:153], v[184:185], v[188:189]
	v_mov_b32_dpp v206, v128 row_shr:1 row_mask:0xf bank_mask:0xf
	v_mov_b32_dpp v207, v129 row_shr:1 row_mask:0xf bank_mask:0xf
	v_pk_fma_f32 v[248:249], v[180:181], v[198:199], v[248:249]
	v_mov_b32_dpp v194, v148 row_shr:1 row_mask:0xf bank_mask:0xf
	v_pk_fma_f32 v[206:207], v[176:177], v[206:207], v[248:249]
	v_mov_b32_dpp v195, v149 row_shr:1 row_mask:0xf bank_mask:0xf
	v_exp_f32_e32 v248, v206
	v_exp_f32_e32 v249, v207
	v_pk_fma_f32 v[250:251], v[156:157], v[168:169], v[172:173]
	v_pk_add_f32 v[248:249], v[248:249], 1.0 op_sel_hi:[1,0]
	v_rcp_f32_e32 v248, v248
	v_rcp_f32_e32 v249, v249
	v_mov_b32_dpp v202, v136 row_shr:1 row_mask:0xf bank_mask:0xf
	v_mov_b32_dpp v203, v137 row_shr:1 row_mask:0xf bank_mask:0xf
	v_pk_fma_f32 v[250:251], v[164:165], v[194:195], v[250:251]
	v_pk_mul_f32 v[206:207], v[206:207], v[248:249]
	v_pk_fma_f32 v[202:203], v[160:161], v[202:203], v[250:251]
	v_mov_b32_dpp v200, v142 row_shr:1 row_mask:0xf bank_mask:0xf
	v_mov_b32_dpp v201, v143 row_shr:1 row_mask:0xf bank_mask:0xf
	v_pk_mul_f32 v[202:203], v[202:203], v[206:207]
	v_pk_fma_f32 v[206:207], v[154:155], v[186:187], v[190:191]
	v_mov_b32_dpp v208, v130 row_shr:1 row_mask:0xf bank_mask:0xf
	v_mov_b32_dpp v209, v131 row_shr:1 row_mask:0xf bank_mask:0xf
	v_pk_fma_f32 v[206:207], v[182:183], v[200:201], v[206:207]
	v_mov_b32_dpp v196, v150 row_shr:1 row_mask:0xf bank_mask:0xf
	v_pk_fma_f32 v[206:207], v[178:179], v[208:209], v[206:207]
	v_mov_b32_dpp v197, v151 row_shr:1 row_mask:0xf bank_mask:0xf
	v_exp_f32_e32 v193, v206
	v_exp_f32_e32 v209, v207
	v_cvt_pk_bf16_f32 v247, v202, v203
	v_add_f32_e32 v193, 1.0, v193
	v_rcp_f32_e32 v202, v193
	v_add_f32_e32 v193, 1.0, v209
	v_rcp_f32_e32 v203, v193
	v_pk_fma_f32 v[248:249], v[158:159], v[170:171], v[174:175]
	v_mov_b32_dpp v204, v138 row_shr:1 row_mask:0xf bank_mask:0xf
	v_mov_b32_dpp v205, v139 row_shr:1 row_mask:0xf bank_mask:0xf
	v_pk_fma_f32 v[248:249], v[166:167], v[196:197], v[248:249]
	v_pk_mul_f32 v[202:203], v[206:207], v[202:203]
	v_pk_fma_f32 v[204:205], v[162:163], v[204:205], v[248:249]
	v_lshl_add_u32 v246, s40, 8, v236
	v_pk_mul_f32 v[202:203], v[204:205], v[202:203]
	v_lshlrev_b64 v[204:205], 1, v[232:233]
	v_pk_fma_f32 v[232:233], v[132:133], v[184:185], v[188:189]
	v_mov_b64_e32 v[206:207], s[60:61]
	v_pk_fma_f32 v[232:233], v[152:153], v[180:181], v[232:233]
	v_cvt_pk_bf16_f32 v248, v202, v203
	v_pk_fma_f32 v[198:199], v[176:177], v[198:199], v[232:233]
	v_mad_i64_i32 v[202:203], s[40:41], v246, s76, v[206:207]
	v_exp_f32_e32 v193, v198
	v_exp_f32_e32 v232, v199
	v_lshl_add_u64 v[202:203], v[202:203], 0, v[204:205]
	v_add_f32_e32 v193, 1.0, v193
	v_rcp_f32_e32 v208, v193
	v_add_f32_e32 v193, 1.0, v232
	v_rcp_f32_e32 v209, v193
	v_pk_fma_f32 v[232:233], v[144:145], v[168:169], v[172:173]
	v_pk_fma_f32 v[140:141], v[140:141], v[184:185], v[188:189]
	v_pk_fma_f32 v[232:233], v[156:157], v[164:165], v[232:233]
	v_pk_mul_f32 v[198:199], v[198:199], v[208:209]
	v_pk_fma_f32 v[194:195], v[160:161], v[194:195], v[232:233]
	v_pk_fma_f32 v[208:209], v[146:147], v[170:171], v[174:175]
	v_pk_mul_f32 v[194:195], v[194:195], v[198:199]
	v_pk_fma_f32 v[198:199], v[134:135], v[186:187], v[190:191]
	v_pk_fma_f32 v[208:209], v[158:159], v[166:167], v[208:209]
	v_pk_fma_f32 v[198:199], v[154:155], v[182:183], v[198:199]
	v_pk_fma_f32 v[196:197], v[162:163], v[196:197], v[208:209]
	v_pk_fma_f32 v[198:199], v[178:179], v[200:201], v[198:199]
	v_cvt_pk_bf16_f32 v249, v194, v195
	v_exp_f32_e32 v200, v198
	v_exp_f32_e32 v201, v199
	v_pk_fma_f32 v[148:149], v[148:149], v[168:169], v[172:173]
	v_pk_add_f32 v[200:201], v[200:201], 1.0 op_sel_hi:[1,0]
	v_rcp_f32_e32 v200, v200
	v_rcp_f32_e32 v201, v201
	v_or_b32_e32 v193, 1, v246
	v_pk_mul_f32 v[198:199], v[198:199], v[200:201]
	s_nop 0
	v_pk_mul_f32 v[196:197], v[196:197], v[198:199]
	v_pk_fma_f32 v[198:199], v[128:129], v[184:185], v[188:189]
	v_cvt_pk_bf16_f32 v250, v196, v197
	v_pk_fma_f32 v[198:199], v[132:133], v[180:181], v[198:199]
	v_mad_i64_i32 v[196:197], s[40:41], v193, s76, v[206:207]
	v_pk_fma_f32 v[152:153], v[152:153], v[176:177], v[198:199]
	v_lshl_add_u64 v[196:197], v[196:197], 0, v[204:205]
	v_exp_f32_e32 v193, v152
	v_exp_f32_e32 v198, v153
	v_add_f32_e32 v193, 1.0, v193
	v_rcp_f32_e32 v194, v193
	v_add_f32_e32 v193, 1.0, v198
	v_rcp_f32_e32 v195, v193
	v_pk_fma_f32 v[198:199], v[136:137], v[168:169], v[172:173]
	v_pk_fma_f32 v[128:129], v[128:129], v[180:181], v[140:141]
	v_pk_fma_f32 v[198:199], v[144:145], v[164:165], v[198:199]
	v_pk_fma_f32 v[128:129], v[132:133], v[176:177], v[128:129]
	v_pk_fma_f32 v[156:157], v[156:157], v[160:161], v[198:199]
	v_pk_mul_f32 v[152:153], v[152:153], v[194:195]
	v_pk_mul_f32 v[152:153], v[156:157], v[152:153]
	v_pk_fma_f32 v[156:157], v[130:131], v[186:187], v[190:191]
	v_exp_f32_e32 v140, v128
	v_pk_fma_f32 v[132:133], v[142:143], v[186:187], v[190:191]
	v_pk_fma_f32 v[156:157], v[134:135], v[182:183], v[156:157]
	v_pk_fma_f32 v[130:131], v[130:131], v[182:183], v[132:133]
	v_pk_fma_f32 v[154:155], v[154:155], v[178:179], v[156:157]
	v_pk_fma_f32 v[130:131], v[134:135], v[178:179], v[130:131]
	v_exp_f32_e32 v157, v154
	v_exp_f32_e32 v141, v129
	v_exp_f32_e32 v132, v130
	v_exp_f32_e32 v133, v131
	v_exp_f32_e32 v193, v155
	v_pk_add_f32 v[140:141], v[140:141], 1.0 op_sel_hi:[1,0]
	v_pk_add_f32 v[132:133], v[132:133], 1.0 op_sel_hi:[1,0]
	v_cvt_pk_bf16_f32 v254, v152, v153
	v_add_f32_e32 v152, 1.0, v157
	v_add_f32_e32 v153, 1.0, v193
	v_rcp_f32_e32 v140, v140
	v_rcp_f32_e32 v141, v141
	v_rcp_f32_e32 v132, v132
; #define LAS __attribute__((address_space(3)))
; __device__ __forceinline__ float sigmoidf_(float x) { return __builtin_amdgcn_rcpf(1.0f + __expf(-x)); }
;     __device__ __forceinline__ void operator()(AccRef acc, const Unit& u, int wr, int wc, int fr, int fq) const {
;     ...
;                 f32x4 h2v = (f32x4){0.f, 0.f, 0.f, 0.f}, h3v = h2v, h2g = h2v, h3g = h2v;
;                 const int pb = ai * 2 + wr - 1;
;                 if (pb >= 0 && fr == 0) { const LAS float* xp = xch + (pb * 2) * 256 + clb + 4 * n;
;                     h2v = *(const LAS f32x4*)(xp); h3v = *(const LAS f32x4*)(xp + 256); h2g = *(const LAS f32x4*)(xp + 128); h3g = *(const LAS f32x4*)(xp + 256 + 128); }
;                 float o[4][4];
; #pragma unroll
;                 for (int j = 0; j < 4; ++j) {
;                     const float v0 = acc[ai][0][0][n][j], v1 = acc[ai][0][1][n][j], v2 = acc[ai][0][2][n][j], v3 = acc[ai][0][3][n][j];
;                     const float g0 = acc[ai][1][0][n][j], g1 = acc[ai][1][1][n][j], g2 = acc[ai][1][2][n][j], g3 = acc[ai][1][3][n][j];
;                     const float pv3 = dpp_upd<0x111>(h3v[j], v3), pv2 = dpp_upd<0x111>(h2v[j], v2), pg3 = dpp_upd<0x111>(h3g[j], g3), pg2 = dpp_upd<0x111>(h2g[j], g2);
;                     const float hv0 = bvv[j] + w2v[j] * v0 + w1v[j] * pv3 + w0v[j] * pv2, hv1 = bvv[j] + w2v[j] * v1 + w1v[j] * v0 + w0v[j] * pv3;
;                     const float hv2 = bvv[j] + w2v[j] * v2 + w1v[j] * v1 + w0v[j] * v0, hv3 = bvv[j] + w2v[j] * v3 + w1v[j] * v2 + w0v[j] * v1;
;                     const float hg0 = bvg[j] + w2g[j] * g0 + w1g[j] * pg3 + w0g[j] * pg2, hg1 = bvg[j] + w2g[j] * g1 + w1g[j] * g0 + w0g[j] * pg3;
;                     const float hg2 = bvg[j] + w2g[j] * g2 + w1g[j] * g1 + w0g[j] * g0, hg3 = bvg[j] + w2g[j] * g3 + w1g[j] * g2 + w0g[j] * g1;
;                     o[0][j] = hg0 * sigmoidf_(hg0) * hv0; o[1][j] = hg1 * sigmoidf_(hg1) * hv1; o[2][j] = hg2 * sigmoidf_(hg2) * hv2; o[3][j] = hg3 * sigmoidf_(hg3) * hv3; }
; #pragma unroll
;                 for (int m = 0; m < 4; ++m) { u32x2 w; w.x = cvt_pk_bf16(o[m][0], o[m][1]); w.y = cvt_pk_bf16(o[m][2], o[m][3]);
;                     *(u32x2*)(Aout + (size_t)(row0 + ai * 128 + m) * FH + hc0 + 4 * n) = w; } } }
	v_rcp_f32_e32 v133, v133
	v_rcp_f32_e32 v152, v152
	v_rcp_f32_e32 v153, v153
	v_pk_fma_f32 v[142:143], v[150:151], v[170:171], v[174:175]
	v_pk_fma_f32 v[194:195], v[138:139], v[170:171], v[174:175]
	v_pk_fma_f32 v[136:137], v[136:137], v[164:165], v[148:149]
	v_pk_fma_f32 v[134:135], v[138:139], v[166:167], v[142:143]
	v_pk_fma_f32 v[194:195], v[146:147], v[166:167], v[194:195]
	v_pk_fma_f32 v[136:137], v[144:145], v[160:161], v[136:137]
	v_pk_mul_f32 v[128:129], v[128:129], v[140:141]
	v_pk_fma_f32 v[134:135], v[146:147], v[162:163], v[134:135]
	v_pk_mul_f32 v[130:131], v[130:131], v[132:133]
	v_pk_fma_f32 v[158:159], v[158:159], v[162:163], v[194:195]
	v_pk_mul_f32 v[152:153], v[154:155], v[152:153]
	v_pk_mul_f32 v[128:129], v[136:137], v[128:129]
	v_pk_mul_f32 v[130:131], v[134:135], v[130:131]
	v_pk_mul_f32 v[152:153], v[158:159], v[152:153]
	v_cvt_pk_bf16_f32 v251, v128, v129
	v_cvt_pk_bf16_f32 v253, v130, v131
	v_or_b32_e32 v130, 3, v246
	v_cvt_pk_bf16_f32 v255, v152, v153
	v_or_b32_e32 v152, 2, v246
	v_mad_i64_i32 v[130:131], s[40:41], v130, s76, v[206:207]
	v_mad_i64_i32 v[152:153], s[40:41], v152, s76, v[206:207]
	v_lshl_add_u64 v[140:141], v[130:131], 0, v[204:205]
	v_lshl_add_u64 v[152:153], v[152:153], 0, v[204:205]
	v_mov_b32_e32 v193, 0
	v_mov_b64_e32 v[194:195], 0
	v_mov_b64_e32 v[136:137], 0
	v_mov_b64_e32 v[138:139], 0
	v_mov_b64_e32 v[128:129], 0
	v_mov_b64_e32 v[130:131], 0
	v_mov_b64_e32 v[132:133], 0
	v_mov_b64_e32 v[134:135], 0
	s_barrier
	s_and_saveexec_b64 s[40:41], s[28:29]
	s_cbranch_execz .LBB0_769
	ds_read_b128 v[132:135], v237 offset:2048
	ds_read_b128 v[136:139], v237 offset:2560
	ds_read_b128 v[128:131], v237 offset:3072
	ds_read_b128 v[192:195], v237 offset:3584
.LBB0_769:
	s_or_b64 exec, exec, s[40:41]
	s_waitcnt lgkmcnt(0)
	v_mov_b32_dpp v192, v72 row_shr:1 row_mask:0xf bank_mask:0xf
	v_mov_b32_dpp v193, v73 row_shr:1 row_mask:0xf bank_mask:0xf
	v_pk_fma_f32 v[142:143], v[88:89], v[184:185], v[188:189]
	v_mov_b32_dpp v136, v64 row_shr:1 row_mask:0xf bank_mask:0xf
	v_mov_b32_dpp v137, v65 row_shr:1 row_mask:0xf bank_mask:0xf
	v_pk_fma_f32 v[142:143], v[180:181], v[192:193], v[142:143]
	v_mov_b32_dpp v128, v84 row_shr:1 row_mask:0xf bank_mask:0xf
	v_pk_fma_f32 v[136:137], v[176:177], v[136:137], v[142:143]
	v_mov_b32_dpp v129, v85 row_shr:1 row_mask:0xf bank_mask:0xf
	v_exp_f32_e32 v142, v136
	v_exp_f32_e32 v143, v137
	v_pk_fma_f32 v[144:145], v[92:93], v[168:169], v[172:173]
	v_mov_b32_dpp v132, v76 row_shr:1 row_mask:0xf bank_mask:0xf
	v_pk_add_f32 v[142:143], v[142:143], 1.0 op_sel_hi:[1,0]
	v_rcp_f32_e32 v142, v142
	v_rcp_f32_e32 v143, v143
	v_mov_b32_dpp v133, v77 row_shr:1 row_mask:0xf bank_mask:0xf
	v_pk_fma_f32 v[144:145], v[164:165], v[128:129], v[144:145]
	v_mov_b32_dpp v194, v74 row_shr:1 row_mask:0xf bank_mask:0xf
	v_pk_fma_f32 v[132:133], v[160:161], v[132:133], v[144:145]
	v_pk_mul_f32 v[136:137], v[136:137], v[142:143]
	v_mov_b32_dpp v195, v75 row_shr:1 row_mask:0xf bank_mask:0xf
	v_pk_mul_f32 v[132:133], v[132:133], v[136:137]
	v_pk_fma_f32 v[136:137], v[90:91], v[186:187], v[190:191]
	v_mov_b32_dpp v138, v66 row_shr:1 row_mask:0xf bank_mask:0xf
	v_mov_b32_dpp v139, v67 row_shr:1 row_mask:0xf bank_mask:0xf
	v_pk_fma_f32 v[136:137], v[182:183], v[194:195], v[136:137]
	v_mov_b32_dpp v130, v86 row_shr:1 row_mask:0xf bank_mask:0xf
	v_pk_fma_f32 v[136:137], v[178:179], v[138:139], v[136:137]
	v_mov_b32_dpp v131, v87 row_shr:1 row_mask:0xf bank_mask:0xf
	v_exp_f32_e32 v139, v136
	v_exp_f32_e32 v142, v137
	v_cvt_pk_bf16_f32 v144, v132, v133
	v_add_f32_e32 v132, 1.0, v139
	v_rcp_f32_e32 v132, v132
	v_add_f32_e32 v133, 1.0, v142
	v_rcp_f32_e32 v133, v133
	v_pk_fma_f32 v[142:143], v[94:95], v[170:171], v[174:175]
	v_mov_b32_dpp v134, v78 row_shr:1 row_mask:0xf bank_mask:0xf
	v_mov_b32_dpp v135, v79 row_shr:1 row_mask:0xf bank_mask:0xf
	v_pk_mul_f32 v[132:133], v[136:137], v[132:133]
	v_pk_fma_f32 v[136:137], v[68:69], v[184:185], v[188:189]
	v_pk_fma_f32 v[142:143], v[166:167], v[130:131], v[142:143]
	v_pk_fma_f32 v[136:137], v[88:89], v[180:181], v[136:137]
	v_pk_fma_f32 v[134:135], v[162:163], v[134:135], v[142:143]
	v_pk_fma_f32 v[136:137], v[176:177], v[192:193], v[136:137]
	v_add_u32_e32 v146, 0x80, v246
	v_exp_f32_e32 v142, v136
	v_exp_f32_e32 v143, v137
	v_pk_mul_f32 v[132:133], v[134:135], v[132:133]
	v_mov_b64_e32 v[134:135], s[60:61]
	v_cvt_pk_bf16_f32 v145, v132, v133
	v_mad_i64_i32 v[132:133], s[40:41], v146, s76, v[134:135]
	v_lshl_add_u64 v[132:133], v[132:133], 0, v[204:205]
	v_add_f32_e32 v138, 1.0, v142
	v_add_f32_e32 v139, 1.0, v143
	v_rcp_f32_e32 v138, v138
	v_rcp_f32_e32 v139, v139
	v_pk_fma_f32 v[142:143], v[80:81], v[168:169], v[172:173]
	v_pk_fma_f32 v[72:73], v[72:73], v[184:185], v[188:189]
	v_pk_fma_f32 v[142:143], v[92:93], v[164:165], v[142:143]
	v_pk_mul_f32 v[136:137], v[136:137], v[138:139]
	v_pk_fma_f32 v[128:129], v[160:161], v[128:129], v[142:143]
	v_pk_fma_f32 v[84:85], v[84:85], v[168:169], v[172:173]
	v_pk_mul_f32 v[128:129], v[128:129], v[136:137]
	v_pk_fma_f32 v[136:137], v[70:71], v[186:187], v[190:191]
	s_nop 0
	v_pk_fma_f32 v[136:137], v[90:91], v[182:183], v[136:137]
	s_nop 0
	v_pk_fma_f32 v[136:137], v[178:179], v[194:195], v[136:137]
	s_nop 0
	v_exp_f32_e32 v139, v136
	v_exp_f32_e32 v142, v137
	v_cvt_pk_bf16_f32 v138, v128, v129
	v_add_f32_e32 v128, 1.0, v139
	v_rcp_f32_e32 v128, v128
	v_add_f32_e32 v129, 1.0, v142
	v_rcp_f32_e32 v129, v129
	v_pk_fma_f32 v[142:143], v[82:83], v[170:171], v[174:175]
	v_pk_mul_f32 v[128:129], v[136:137], v[128:129]
	v_pk_fma_f32 v[142:143], v[94:95], v[166:167], v[142:143]
	v_pk_fma_f32 v[136:137], v[76:77], v[168:169], v[172:173]
; #define LAS __attribute__((address_space(3)))
; __device__ __forceinline__ float sigmoidf_(float x) { return __builtin_amdgcn_rcpf(1.0f + __expf(-x)); }
;     __device__ __forceinline__ void operator()(AccRef acc, const Unit& u, int wr, int wc, int fr, int fq) const {
;     ...
;                 f32x4 h2v = (f32x4){0.f, 0.f, 0.f, 0.f}, h3v = h2v, h2g = h2v, h3g = h2v;
;                 const int pb = ai * 2 + wr - 1;
;                 if (pb >= 0 && fr == 0) { const LAS float* xp = xch + (pb * 2) * 256 + clb + 4 * n;
;                     h2v = *(const LAS f32x4*)(xp); h3v = *(const LAS f32x4*)(xp + 256); h2g = *(const LAS f32x4*)(xp + 128); h3g = *(const LAS f32x4*)(xp + 256 + 128); }
;                 float o[4][4];
; #pragma unroll
;                 for (int j = 0; j < 4; ++j) {
;                     const float v0 = acc[ai][0][0][n][j], v1 = acc[ai][0][1][n][j], v2 = acc[ai][0][2][n][j], v3 = acc[ai][0][3][n][j];
;                     const float g0 = acc[ai][1][0][n][j], g1 = acc[ai][1][1][n][j], g2 = acc[ai][1][2][n][j], g3 = acc[ai][1][3][n][j];
;                     const float pv3 = dpp_upd<0x111>(h3v[j], v3), pv2 = dpp_upd<0x111>(h2v[j], v2), pg3 = dpp_upd<0x111>(h3g[j], g3), pg2 = dpp_upd<0x111>(h2g[j], g2);
;                     const float hv0 = bvv[j] + w2v[j] * v0 + w1v[j] * pv3 + w0v[j] * pv2, hv1 = bvv[j] + w2v[j] * v1 + w1v[j] * v0 + w0v[j] * pv3;
;                     const float hv2 = bvv[j] + w2v[j] * v2 + w1v[j] * v1 + w0v[j] * v0, hv3 = bvv[j] + w2v[j] * v3 + w1v[j] * v2 + w0v[j] * v1;
;                     const float hg0 = bvg[j] + w2g[j] * g0 + w1g[j] * pg3 + w0g[j] * pg2, hg1 = bvg[j] + w2g[j] * g1 + w1g[j] * g0 + w0g[j] * pg3;
;                     const float hg2 = bvg[j] + w2g[j] * g2 + w1g[j] * g1 + w0g[j] * g0, hg3 = bvg[j] + w2g[j] * g3 + w1g[j] * g2 + w0g[j] * g1;
;                     o[0][j] = hg0 * sigmoidf_(hg0) * hv0; o[1][j] = hg1 * sigmoidf_(hg1) * hv1; o[2][j] = hg2 * sigmoidf_(hg2) * hv2; o[3][j] = hg3 * sigmoidf_(hg3) * hv3; }
; #pragma unroll
;                 for (int m = 0; m < 4; ++m) { u32x2 w; w.x = cvt_pk_bf16(o[m][0], o[m][1]); w.y = cvt_pk_bf16(o[m][2], o[m][3]);
;                     *(u32x2*)(Aout + (size_t)(row0 + ai * 128 + m) * FH + hc0 + 4 * n) = w; } } }
	v_pk_fma_f32 v[130:131], v[162:163], v[130:131], v[142:143]
	v_pk_fma_f32 v[136:137], v[80:81], v[164:165], v[136:137]
	v_pk_mul_f32 v[128:129], v[130:131], v[128:129]
	v_pk_fma_f32 v[130:131], v[64:65], v[184:185], v[188:189]
	v_pk_fma_f32 v[64:65], v[64:65], v[180:181], v[72:73]
	v_pk_fma_f32 v[130:131], v[68:69], v[180:181], v[130:131]
	v_pk_fma_f32 v[64:65], v[68:69], v[176:177], v[64:65]
	v_pk_fma_f32 v[88:89], v[88:89], v[176:177], v[130:131]
	v_pk_fma_f32 v[92:93], v[92:93], v[160:161], v[136:137]
	v_exp_f32_e32 v130, v88
	v_exp_f32_e32 v131, v89
	v_exp_f32_e32 v72, v64
	v_pk_add_f32 v[130:131], v[130:131], 1.0 op_sel_hi:[1,0]
	v_rcp_f32_e32 v130, v130
	v_rcp_f32_e32 v131, v131
	v_pk_fma_f32 v[68:69], v[74:75], v[186:187], v[190:191]
	v_exp_f32_e32 v73, v65
	v_pk_mul_f32 v[88:89], v[88:89], v[130:131]
	v_pk_mul_f32 v[88:89], v[92:93], v[88:89]
	v_pk_fma_f32 v[92:93], v[66:67], v[186:187], v[190:191]
	v_pk_fma_f32 v[66:67], v[66:67], v[182:183], v[68:69]
	v_pk_fma_f32 v[92:93], v[70:71], v[182:183], v[92:93]
	v_pk_fma_f32 v[66:67], v[70:71], v[178:179], v[66:67]
	v_pk_fma_f32 v[90:91], v[90:91], v[178:179], v[92:93]
	v_exp_f32_e32 v93, v90
	v_exp_f32_e32 v68, v66
	v_exp_f32_e32 v69, v67
	v_exp_f32_e32 v130, v91
	v_pk_add_f32 v[72:73], v[72:73], 1.0 op_sel_hi:[1,0]
	v_pk_add_f32 v[68:69], v[68:69], 1.0 op_sel_hi:[1,0]
	v_cvt_pk_bf16_f32 v198, v88, v89
	v_add_f32_e32 v88, 1.0, v93
	v_add_f32_e32 v89, 1.0, v130
	v_rcp_f32_e32 v72, v72
	v_rcp_f32_e32 v73, v73
	v_rcp_f32_e32 v68, v68
	v_rcp_f32_e32 v69, v69
	v_rcp_f32_e32 v88, v88
	v_rcp_f32_e32 v89, v89
	v_pk_fma_f32 v[74:75], v[86:87], v[170:171], v[174:175]
	v_pk_fma_f32 v[130:131], v[78:79], v[170:171], v[174:175]
	v_pk_fma_f32 v[76:77], v[76:77], v[164:165], v[84:85]
	v_pk_fma_f32 v[70:71], v[78:79], v[166:167], v[74:75]
	v_pk_fma_f32 v[130:131], v[82:83], v[166:167], v[130:131]
	v_pk_fma_f32 v[76:77], v[80:81], v[160:161], v[76:77]
	v_pk_mul_f32 v[64:65], v[64:65], v[72:73]
	v_pk_fma_f32 v[70:71], v[82:83], v[162:163], v[70:71]
	v_pk_mul_f32 v[66:67], v[66:67], v[68:69]
	v_pk_fma_f32 v[94:95], v[94:95], v[162:163], v[130:131]
	v_pk_mul_f32 v[88:89], v[90:91], v[88:89]
	v_pk_mul_f32 v[64:65], v[76:77], v[64:65]
	v_pk_mul_f32 v[66:67], v[70:71], v[66:67]
	v_pk_mul_f32 v[88:89], v[94:95], v[88:89]
	v_cvt_pk_bf16_f32 v148, v64, v65
	v_cvt_pk_bf16_f32 v149, v66, v67
	v_add_u32_e32 v66, 0x83, v246
	v_cvt_pk_bf16_f32 v155, v128, v129
	v_add_u32_e32 v128, 0x81, v246
	v_cvt_pk_bf16_f32 v199, v88, v89
	v_add_u32_e32 v88, 0x82, v246
	v_mad_i64_i32 v[66:67], s[40:41], v66, s76, v[134:135]
	v_mad_i64_i32 v[128:129], s[40:41], v128, s76, v[134:135]
	v_mad_i64_i32 v[88:89], s[40:41], v88, s76, v[134:135]
	v_lshl_add_u64 v[82:83], v[66:67], 0, v[204:205]
	v_lshl_add_u64 v[128:129], v[128:129], 0, v[204:205]
	v_lshl_add_u64 v[88:89], v[88:89], 0, v[204:205]
	v_mov_b32_e32 v64, 0
	v_mov_b64_e32 v[70:71], 0
	v_mov_b64_e32 v[72:73], 0
	v_mov_b64_e32 v[78:79], 0
	v_mov_b64_e32 v[80:81], 0
	v_mov_b64_e32 v[66:67], 0
	v_mov_b64_e32 v[68:69], 0
	v_mov_b64_e32 v[74:75], 0
	v_mov_b64_e32 v[76:77], 0
	v_mov_b32_e32 v154, v138
	s_barrier
	s_and_saveexec_b64 s[40:41], s[26:27]
	s_cbranch_execz .LBB0_771
	ds_read_b128 v[74:77], v242
	ds_read_b128 v[66:69], v241
	ds_read_b128 v[78:81], v240
	ds_read_b128 v[70:73], v239
; #define LAS __attribute__((address_space(3)))
; __device__ __forceinline__ float sigmoidf_(float x) { return __builtin_amdgcn_rcpf(1.0f + __expf(-x)); }
;     __device__ __forceinline__ void operator()(AccRef acc, const Unit& u, int wr, int wc, int fr, int fq) const {
;     ...
;                 f32x4 h2v = (f32x4){0.f, 0.f, 0.f, 0.f}, h3v = h2v, h2g = h2v, h3g = h2v;
;                 const int pb = ai * 2 + wr - 1;
;                 if (pb >= 0 && fr == 0) { const LAS float* xp = xch + (pb * 2) * 256 + clb + 4 * n;
;                     h2v = *(const LAS f32x4*)(xp); h3v = *(const LAS f32x4*)(xp + 256); h2g = *(const LAS f32x4*)(xp + 128); h3g = *(const LAS f32x4*)(xp + 256 + 128); }
;                 float o[4][4];
; #pragma unroll
;                 for (int j = 0; j < 4; ++j) {
;                     const float v0 = acc[ai][0][0][n][j], v1 = acc[ai][0][1][n][j], v2 = acc[ai][0][2][n][j], v3 = acc[ai][0][3][n][j];
;                     const float g0 = acc[ai][1][0][n][j], g1 = acc[ai][1][1][n][j], g2 = acc[ai][1][2][n][j], g3 = acc[ai][1][3][n][j];
;                     const float pv3 = dpp_upd<0x111>(h3v[j], v3), pv2 = dpp_upd<0x111>(h2v[j], v2), pg3 = dpp_upd<0x111>(h3g[j], g3), pg2 = dpp_upd<0x111>(h2g[j], g2);
;                     const float hv0 = bvv[j] + w2v[j] * v0 + w1v[j] * pv3 + w0v[j] * pv2, hv1 = bvv[j] + w2v[j] * v1 + w1v[j] * v0 + w0v[j] * pv3;
;                     const float hv2 = bvv[j] + w2v[j] * v2 + w1v[j] * v1 + w0v[j] * v0, hv3 = bvv[j] + w2v[j] * v3 + w1v[j] * v2 + w0v[j] * v1;
;                     const float hg0 = bvg[j] + w2g[j] * g0 + w1g[j] * pg3 + w0g[j] * pg2, hg1 = bvg[j] + w2g[j] * g1 + w1g[j] * g0 + w0g[j] * pg3;
;                     const float hg2 = bvg[j] + w2g[j] * g2 + w1g[j] * g1 + w0g[j] * g0, hg3 = bvg[j] + w2g[j] * g3 + w1g[j] * g2 + w0g[j] * g1;
;                     o[0][j] = hg0 * sigmoidf_(hg0) * hv0; o[1][j] = hg1 * sigmoidf_(hg1) * hv1; o[2][j] = hg2 * sigmoidf_(hg2) * hv2; o[3][j] = hg3 * sigmoidf_(hg3) * hv3; }
; #pragma unroll
;                 for (int m = 0; m < 4; ++m) { u32x2 w; w.x = cvt_pk_bf16(o[m][0], o[m][1]); w.y = cvt_pk_bf16(o[m][2], o[m][3]);
;                     *(u32x2*)(Aout + (size_t)(row0 + ai * 128 + m) * FH + hc0 + 4 * n) = w; } } }
.LBB0_771:
	s_or_b64 exec, exec, s[40:41]
	s_waitcnt lgkmcnt(0)
	v_mov_b32_dpp v70, v44 row_shr:1 row_mask:0xf bank_mask:0xf
	v_mov_b32_dpp v71, v45 row_shr:1 row_mask:0xf bank_mask:0xf
	s_waitcnt vmcnt(0)
	v_pk_fma_f32 v[84:85], v[56:57], v[120:121], v[124:125]
	v_mov_b32_dpp v78, v32 row_shr:1 row_mask:0xf bank_mask:0xf
	v_mov_b32_dpp v79, v33 row_shr:1 row_mask:0xf bank_mask:0xf
	v_pk_fma_f32 v[84:85], v[116:117], v[70:71], v[84:85]
	v_mov_b32_dpp v66, v52 row_shr:1 row_mask:0xf bank_mask:0xf
	v_pk_fma_f32 v[78:79], v[112:113], v[78:79], v[84:85]
	v_mov_b32_dpp v67, v53 row_shr:1 row_mask:0xf bank_mask:0xf
	v_exp_f32_e32 v84, v78
	v_exp_f32_e32 v85, v79
	v_pk_fma_f32 v[86:87], v[60:61], v[104:105], v[108:109]
	v_pk_add_f32 v[84:85], v[84:85], 1.0 op_sel_hi:[1,0]
	v_rcp_f32_e32 v84, v84
	v_rcp_f32_e32 v85, v85
	v_mov_b32_dpp v74, v40 row_shr:1 row_mask:0xf bank_mask:0xf
	v_mov_b32_dpp v75, v41 row_shr:1 row_mask:0xf bank_mask:0xf
	v_pk_fma_f32 v[86:87], v[100:101], v[66:67], v[86:87]
	v_pk_mul_f32 v[78:79], v[78:79], v[84:85]
	v_pk_fma_f32 v[74:75], v[96:97], v[74:75], v[86:87]
	v_mov_b32_dpp v72, v46 row_shr:1 row_mask:0xf bank_mask:0xf
	v_mov_b32_dpp v73, v47 row_shr:1 row_mask:0xf bank_mask:0xf
	v_pk_mul_f32 v[74:75], v[74:75], v[78:79]
	v_pk_fma_f32 v[78:79], v[58:59], v[122:123], v[126:127]
	v_mov_b32_dpp v80, v34 row_shr:1 row_mask:0xf bank_mask:0xf
	v_mov_b32_dpp v81, v35 row_shr:1 row_mask:0xf bank_mask:0xf
	v_pk_fma_f32 v[78:79], v[118:119], v[72:73], v[78:79]
	v_mov_b32_dpp v68, v54 row_shr:1 row_mask:0xf bank_mask:0xf
	v_pk_fma_f32 v[78:79], v[114:115], v[80:81], v[78:79]
	v_mov_b32_dpp v69, v55 row_shr:1 row_mask:0xf bank_mask:0xf
	v_exp_f32_e32 v80, v78
	v_exp_f32_e32 v81, v79
	v_pk_fma_f32 v[84:85], v[62:63], v[106:107], v[110:111]
	v_pk_add_f32 v[80:81], v[80:81], 1.0 op_sel_hi:[1,0]
	v_rcp_f32_e32 v80, v80
	v_rcp_f32_e32 v81, v81
	v_mov_b32_dpp v76, v42 row_shr:1 row_mask:0xf bank_mask:0xf
	v_mov_b32_dpp v77, v43 row_shr:1 row_mask:0xf bank_mask:0xf
	v_pk_fma_f32 v[84:85], v[102:103], v[68:69], v[84:85]
	v_pk_mul_f32 v[78:79], v[78:79], v[80:81]
	v_pk_fma_f32 v[76:77], v[98:99], v[76:77], v[84:85]
	v_cvt_pk_bf16_f32 v92, v74, v75
	v_pk_mul_f32 v[76:77], v[76:77], v[78:79]
	v_pk_fma_f32 v[44:45], v[44:45], v[120:121], v[124:125]
	v_cvt_pk_bf16_f32 v93, v76, v77
	v_pk_fma_f32 v[76:77], v[36:37], v[120:121], v[124:125]
	v_mov_b32_e32 v90, v247
	v_mov_b32_e32 v91, v248
	global_store_dwordx4 v[202:203], v[90:93], off
	v_pk_fma_f32 v[76:77], v[56:57], v[116:117], v[76:77]
	v_pk_fma_f32 v[52:53], v[52:53], v[104:105], v[108:109]
	v_pk_fma_f32 v[70:71], v[112:113], v[70:71], v[76:77]
	s_nop 0
	v_exp_f32_e32 v74, v70
	v_exp_f32_e32 v75, v71
	s_nop 0
	v_pk_add_f32 v[74:75], v[74:75], 1.0 op_sel_hi:[1,0]
	v_rcp_f32_e32 v74, v74
	v_rcp_f32_e32 v75, v75
	v_pk_fma_f32 v[76:77], v[48:49], v[104:105], v[108:109]
	v_pk_mul_f32 v[70:71], v[70:71], v[74:75]
	v_pk_fma_f32 v[76:77], v[60:61], v[100:101], v[76:77]
	v_pk_fma_f32 v[74:75], v[50:51], v[106:107], v[110:111]
	v_pk_fma_f32 v[66:67], v[96:97], v[66:67], v[76:77]
	v_pk_fma_f32 v[74:75], v[62:63], v[102:103], v[74:75]
	v_pk_mul_f32 v[66:67], v[66:67], v[70:71]
	v_pk_fma_f32 v[70:71], v[38:39], v[122:123], v[126:127]
	v_pk_fma_f32 v[68:69], v[98:99], v[68:69], v[74:75]
	v_pk_fma_f32 v[70:71], v[58:59], v[118:119], v[70:71]
	v_cvt_pk_bf16_f32 v136, v66, v67
	v_pk_fma_f32 v[70:71], v[114:115], v[72:73], v[70:71]
	s_nop 0
	v_exp_f32_e32 v72, v70
	v_exp_f32_e32 v73, v71
	s_nop 0
	v_pk_add_f32 v[72:73], v[72:73], 1.0 op_sel_hi:[1,0]
	v_rcp_f32_e32 v72, v72
	v_rcp_f32_e32 v73, v73
	s_nop 0
	v_pk_mul_f32 v[70:71], v[70:71], v[72:73]
	s_nop 0
	v_pk_mul_f32 v[68:69], v[68:69], v[70:71]
	s_nop 0
	v_cvt_pk_bf16_f32 v137, v68, v69
	v_pk_fma_f32 v[68:69], v[32:33], v[120:121], v[124:125]
	v_mov_b32_e32 v134, v249
	v_mov_b32_e32 v135, v250
	global_store_dwordx4 v[196:197], v[134:137], off
	v_pk_fma_f32 v[68:69], v[36:37], v[116:117], v[68:69]
	v_pk_fma_f32 v[32:33], v[32:33], v[116:117], v[44:45]
	v_pk_fma_f32 v[56:57], v[56:57], v[112:113], v[68:69]
	v_pk_fma_f32 v[32:33], v[36:37], v[112:113], v[32:33]
	v_exp_f32_e32 v66, v56
	v_exp_f32_e32 v67, v57
	s_nop 0
	v_pk_add_f32 v[66:67], v[66:67], 1.0 op_sel_hi:[1,0]
	v_rcp_f32_e32 v66, v66
	v_rcp_f32_e32 v67, v67
	v_pk_fma_f32 v[68:69], v[40:41], v[104:105], v[108:109]
	v_exp_f32_e32 v44, v32
	v_pk_fma_f32 v[68:69], v[48:49], v[100:101], v[68:69]
	v_pk_mul_f32 v[56:57], v[56:57], v[66:67]
	v_pk_fma_f32 v[60:61], v[60:61], v[96:97], v[68:69]
	v_pk_fma_f32 v[36:37], v[46:47], v[122:123], v[126:127]
	v_pk_mul_f32 v[56:57], v[60:61], v[56:57]
	v_pk_fma_f32 v[60:61], v[34:35], v[122:123], v[126:127]
	v_pk_fma_f32 v[34:35], v[34:35], v[118:119], v[36:37]
	v_pk_fma_f32 v[60:61], v[38:39], v[118:119], v[60:61]
	v_pk_fma_f32 v[34:35], v[38:39], v[114:115], v[34:35]
	v_pk_fma_f32 v[58:59], v[58:59], v[114:115], v[60:61]
	v_exp_f32_e32 v60, v58
	v_exp_f32_e32 v45, v33
	v_exp_f32_e32 v36, v34
	v_exp_f32_e32 v37, v35
	v_exp_f32_e32 v61, v59
	v_cvt_pk_bf16_f32 v164, v56, v57
	v_pk_add_f32 v[44:45], v[44:45], 1.0 op_sel_hi:[1,0]
	v_pk_add_f32 v[36:37], v[36:37], 1.0 op_sel_hi:[1,0]
	v_pk_add_f32 v[60:61], v[60:61], 1.0 op_sel_hi:[1,0]
	v_rcp_f32_e32 v44, v44
	v_rcp_f32_e32 v45, v45
	v_rcp_f32_e32 v36, v36
	v_rcp_f32_e32 v37, v37
	v_rcp_f32_e32 v60, v60
	v_rcp_f32_e32 v61, v61
	v_pk_fma_f32 v[46:47], v[54:55], v[106:107], v[110:111]
	v_pk_fma_f32 v[66:67], v[42:43], v[106:107], v[110:111]
	v_pk_fma_f32 v[40:41], v[40:41], v[100:101], v[52:53]
	v_pk_fma_f32 v[38:39], v[42:43], v[102:103], v[46:47]
	v_pk_fma_f32 v[66:67], v[50:51], v[102:103], v[66:67]
	v_pk_fma_f32 v[40:41], v[48:49], v[96:97], v[40:41]
	v_pk_mul_f32 v[32:33], v[32:33], v[44:45]
	v_pk_fma_f32 v[38:39], v[50:51], v[98:99], v[38:39]
	v_pk_mul_f32 v[34:35], v[34:35], v[36:37]
	v_pk_fma_f32 v[62:63], v[62:63], v[98:99], v[66:67]
	v_pk_mul_f32 v[58:59], v[58:59], v[60:61]
	v_pk_mul_f32 v[32:33], v[40:41], v[32:33]
	v_pk_mul_f32 v[34:35], v[38:39], v[34:35]
	v_pk_mul_f32 v[58:59], v[62:63], v[58:59]
	v_cvt_pk_bf16_f32 v160, v32, v33
	v_cvt_pk_bf16_f32 v161, v34, v35
	v_cvt_pk_bf16_f32 v57, v58, v59
	v_mov_b32_e32 v158, v251
	v_mov_b32_e32 v159, v253
	global_store_dwordx4 v[140:141], v[158:161], off
	v_mov_b32_e32 v65, 0
	v_mov_b64_e32 v[66:67], 0
	v_mov_b64_e32 v[40:41], 0
	v_mov_b64_e32 v[42:43], 0
	v_mov_b64_e32 v[32:33], 0
	v_mov_b64_e32 v[34:35], 0
	v_mov_b64_e32 v[36:37], 0
	v_mov_b64_e32 v[38:39], 0
	v_mov_b32_e32 v162, v254
	v_mov_b32_e32 v163, v255
	v_mov_b32_e32 v165, v57
	global_store_dwordx4 v[152:153], v[162:165], off
	s_barrier
	s_and_saveexec_b64 s[40:41], s[28:29]
	s_cbranch_execz .LBB0_754
	ds_read_b128 v[36:39], v237 offset:2064
	ds_read_b128 v[40:43], v237 offset:2576
	ds_read_b128 v[32:35], v237 offset:3088
	ds_read_b128 v[64:67], v237 offset:3600
	s_branch .LBB0_754

; #define LAS __attribute__((address_space(3)))
; __device__ __forceinline__ float sigmoidf_(float x) { return __builtin_amdgcn_rcpf(1.0f + __expf(-x)); }
;     __device__ __forceinline__ void operator()(AccRef acc, const Unit& u, int wr, int wc, int fr, int fq) const {
;     ...
;                 f32x4 h2v = (f32x4){0.f, 0.f, 0.f, 0.f}, h3v = h2v, h2g = h2v, h3g = h2v;
;                 const int pb = ai * 2 + wr - 1;
;                 if (pb >= 0 && fr == 0) { const LAS float* xp = xch + (pb * 2) * 256 + clb + 4 * n;
;                     h2v = *(const LAS f32x4*)(xp); h3v = *(const LAS f32x4*)(xp + 256); h2g = *(const LAS f32x4*)(xp + 128); h3g = *(const LAS f32x4*)(xp + 256 + 128); }
;                 float o[4][4];
; #pragma unroll
;                 for (int j = 0; j < 4; ++j) {
;                     const float v0 = acc[ai][0][0][n][j], v1 = acc[ai][0][1][n][j], v2 = acc[ai][0][2][n][j], v3 = acc[ai][0][3][n][j];
;                     const float g0 = acc[ai][1][0][n][j], g1 = acc[ai][1][1][n][j], g2 = acc[ai][1][2][n][j], g3 = acc[ai][1][3][n][j];
;                     const float pv3 = dpp_upd<0x111>(h3v[j], v3), pv2 = dpp_upd<0x111>(h2v[j], v2), pg3 = dpp_upd<0x111>(h3g[j], g3), pg2 = dpp_upd<0x111>(h2g[j], g2);
;                     const float hv0 = bvv[j] + w2v[j] * v0 + w1v[j] * pv3 + w0v[j] * pv2, hv1 = bvv[j] + w2v[j] * v1 + w1v[j] * v0 + w0v[j] * pv3;
;                     const float hv2 = bvv[j] + w2v[j] * v2 + w1v[j] * v1 + w0v[j] * v0, hv3 = bvv[j] + w2v[j] * v3 + w1v[j] * v2 + w0v[j] * v1;
;                     const float hg0 = bvg[j] + w2g[j] * g0 + w1g[j] * pg3 + w0g[j] * pg2, hg1 = bvg[j] + w2g[j] * g1 + w1g[j] * g0 + w0g[j] * pg3;
;                     const float hg2 = bvg[j] + w2g[j] * g2 + w1g[j] * g1 + w0g[j] * g0, hg3 = bvg[j] + w2g[j] * g3 + w1g[j] * g2 + w0g[j] * g1;
;                     o[0][j] = hg0 * sigmoidf_(hg0) * hv0; o[1][j] = hg1 * sigmoidf_(hg1) * hv1; o[2][j] = hg2 * sigmoidf_(hg2) * hv2; o[3][j] = hg3 * sigmoidf_(hg3) * hv3; }
; #pragma unroll
;                 for (int m = 0; m < 4; ++m) { u32x2 w; w.x = cvt_pk_bf16(o[m][0], o[m][1]); w.y = cvt_pk_bf16(o[m][2], o[m][3]);
;                     *(u32x2*)(Aout + (size_t)(row0 + ai * 128 + m) * FH + hc0 + 4 * n) = w; } } }
.LBB0_1366:
	s_or_b64 exec, exec, s[48:49]
	v_pk_fma_f32 v[248:249], v[152:153], v[184:185], v[188:189]
	v_mov_b32_dpp v206, v128 row_shr:1 row_mask:0xf bank_mask:0xf
	v_mov_b32_dpp v207, v129 row_shr:1 row_mask:0xf bank_mask:0xf
	v_pk_fma_f32 v[248:249], v[180:181], v[198:199], v[248:249]
	v_mov_b32_dpp v194, v148 row_shr:1 row_mask:0xf bank_mask:0xf
	v_pk_fma_f32 v[206:207], v[176:177], v[206:207], v[248:249]
	v_mov_b32_dpp v195, v149 row_shr:1 row_mask:0xf bank_mask:0xf
	v_exp_f32_e32 v248, v206
	v_exp_f32_e32 v249, v207
	v_pk_fma_f32 v[250:251], v[156:157], v[168:169], v[172:173]
	v_pk_add_f32 v[248:249], v[248:249], 1.0 op_sel_hi:[1,0]
	v_rcp_f32_e32 v248, v248
	v_rcp_f32_e32 v249, v249
	v_mov_b32_dpp v202, v136 row_shr:1 row_mask:0xf bank_mask:0xf
	v_mov_b32_dpp v203, v137 row_shr:1 row_mask:0xf bank_mask:0xf
	v_pk_fma_f32 v[250:251], v[164:165], v[194:195], v[250:251]
	v_pk_mul_f32 v[206:207], v[206:207], v[248:249]
	v_pk_fma_f32 v[202:203], v[160:161], v[202:203], v[250:251]
	v_mov_b32_dpp v200, v142 row_shr:1 row_mask:0xf bank_mask:0xf
	v_mov_b32_dpp v201, v143 row_shr:1 row_mask:0xf bank_mask:0xf
	v_pk_mul_f32 v[202:203], v[202:203], v[206:207]
	v_pk_fma_f32 v[206:207], v[154:155], v[186:187], v[190:191]
	v_mov_b32_dpp v208, v130 row_shr:1 row_mask:0xf bank_mask:0xf
	v_mov_b32_dpp v209, v131 row_shr:1 row_mask:0xf bank_mask:0xf
	v_pk_fma_f32 v[206:207], v[182:183], v[200:201], v[206:207]
	v_mov_b32_dpp v196, v150 row_shr:1 row_mask:0xf bank_mask:0xf
	v_pk_fma_f32 v[206:207], v[178:179], v[208:209], v[206:207]
	v_mov_b32_dpp v197, v151 row_shr:1 row_mask:0xf bank_mask:0xf
	v_exp_f32_e32 v193, v206
	v_exp_f32_e32 v209, v207
	v_cvt_pk_bf16_f32 v247, v202, v203
	v_add_f32_e32 v193, 1.0, v193
	v_rcp_f32_e32 v202, v193
	v_add_f32_e32 v193, 1.0, v209
	v_rcp_f32_e32 v203, v193
	v_pk_fma_f32 v[248:249], v[158:159], v[170:171], v[174:175]
	v_mov_b32_dpp v204, v138 row_shr:1 row_mask:0xf bank_mask:0xf
	v_mov_b32_dpp v205, v139 row_shr:1 row_mask:0xf bank_mask:0xf
	v_pk_fma_f32 v[248:249], v[166:167], v[196:197], v[248:249]
	v_pk_mul_f32 v[202:203], v[206:207], v[202:203]
	v_pk_fma_f32 v[204:205], v[162:163], v[204:205], v[248:249]
	v_lshl_add_u32 v246, s42, 8, v236
	v_pk_mul_f32 v[202:203], v[204:205], v[202:203]
	v_lshlrev_b64 v[204:205], 1, v[232:233]
	v_pk_fma_f32 v[232:233], v[132:133], v[184:185], v[188:189]
	v_mov_b64_e32 v[206:207], s[60:61]
	v_pk_fma_f32 v[232:233], v[152:153], v[180:181], v[232:233]
	v_cvt_pk_bf16_f32 v248, v202, v203
	v_pk_fma_f32 v[198:199], v[176:177], v[198:199], v[232:233]
	v_mad_i64_i32 v[202:203], s[42:43], v246, s82, v[206:207]
	v_exp_f32_e32 v193, v198
	v_exp_f32_e32 v232, v199
	v_lshl_add_u64 v[202:203], v[202:203], 0, v[204:205]
	v_add_f32_e32 v193, 1.0, v193
	v_rcp_f32_e32 v208, v193
	v_add_f32_e32 v193, 1.0, v232
	v_rcp_f32_e32 v209, v193
	v_pk_fma_f32 v[232:233], v[144:145], v[168:169], v[172:173]
	v_pk_fma_f32 v[140:141], v[140:141], v[184:185], v[188:189]
	v_pk_fma_f32 v[232:233], v[156:157], v[164:165], v[232:233]
	v_pk_mul_f32 v[198:199], v[198:199], v[208:209]
	v_pk_fma_f32 v[194:195], v[160:161], v[194:195], v[232:233]
	v_pk_fma_f32 v[208:209], v[146:147], v[170:171], v[174:175]
	v_pk_mul_f32 v[194:195], v[194:195], v[198:199]
	v_pk_fma_f32 v[198:199], v[134:135], v[186:187], v[190:191]
	v_pk_fma_f32 v[208:209], v[158:159], v[166:167], v[208:209]
	v_pk_fma_f32 v[198:199], v[154:155], v[182:183], v[198:199]
	v_pk_fma_f32 v[196:197], v[162:163], v[196:197], v[208:209]
	v_pk_fma_f32 v[198:199], v[178:179], v[200:201], v[198:199]
	v_cvt_pk_bf16_f32 v249, v194, v195
	v_exp_f32_e32 v200, v198
	v_exp_f32_e32 v201, v199
	v_pk_fma_f32 v[148:149], v[148:149], v[168:169], v[172:173]
	v_pk_add_f32 v[200:201], v[200:201], 1.0 op_sel_hi:[1,0]
	v_rcp_f32_e32 v200, v200
	v_rcp_f32_e32 v201, v201
	v_or_b32_e32 v193, 1, v246
	v_pk_mul_f32 v[198:199], v[198:199], v[200:201]
	s_nop 0
	v_pk_mul_f32 v[196:197], v[196:197], v[198:199]
	v_pk_fma_f32 v[198:199], v[128:129], v[184:185], v[188:189]
	v_cvt_pk_bf16_f32 v250, v196, v197
	v_pk_fma_f32 v[198:199], v[132:133], v[180:181], v[198:199]
	v_mad_i64_i32 v[196:197], s[42:43], v193, s82, v[206:207]
	v_pk_fma_f32 v[152:153], v[152:153], v[176:177], v[198:199]
	v_lshl_add_u64 v[196:197], v[196:197], 0, v[204:205]
	v_exp_f32_e32 v193, v152
	v_exp_f32_e32 v198, v153
	v_add_f32_e32 v193, 1.0, v193
	v_rcp_f32_e32 v194, v193
	v_add_f32_e32 v193, 1.0, v198
	v_rcp_f32_e32 v195, v193
	v_pk_fma_f32 v[198:199], v[136:137], v[168:169], v[172:173]
	v_pk_fma_f32 v[128:129], v[128:129], v[180:181], v[140:141]
	v_pk_fma_f32 v[198:199], v[144:145], v[164:165], v[198:199]
	v_pk_fma_f32 v[128:129], v[132:133], v[176:177], v[128:129]
	v_pk_fma_f32 v[156:157], v[156:157], v[160:161], v[198:199]
	v_pk_mul_f32 v[152:153], v[152:153], v[194:195]
	v_pk_mul_f32 v[152:153], v[156:157], v[152:153]
	v_pk_fma_f32 v[156:157], v[130:131], v[186:187], v[190:191]
	v_exp_f32_e32 v140, v128
	v_pk_fma_f32 v[132:133], v[142:143], v[186:187], v[190:191]
	v_pk_fma_f32 v[156:157], v[134:135], v[182:183], v[156:157]
	v_pk_fma_f32 v[130:131], v[130:131], v[182:183], v[132:133]
	v_pk_fma_f32 v[154:155], v[154:155], v[178:179], v[156:157]
	v_pk_fma_f32 v[130:131], v[134:135], v[178:179], v[130:131]
	v_exp_f32_e32 v157, v154
	v_exp_f32_e32 v141, v129
	v_exp_f32_e32 v132, v130
	v_exp_f32_e32 v133, v131
	v_exp_f32_e32 v193, v155
	v_pk_add_f32 v[140:141], v[140:141], 1.0 op_sel_hi:[1,0]
	v_pk_add_f32 v[132:133], v[132:133], 1.0 op_sel_hi:[1,0]
	v_cvt_pk_bf16_f32 v254, v152, v153
	v_add_f32_e32 v152, 1.0, v157
	v_add_f32_e32 v153, 1.0, v193
	v_rcp_f32_e32 v140, v140
	v_rcp_f32_e32 v141, v141
	v_rcp_f32_e32 v132, v132
; #define LAS __attribute__((address_space(3)))
; __device__ __forceinline__ float sigmoidf_(float x) { return __builtin_amdgcn_rcpf(1.0f + __expf(-x)); }
;     __device__ __forceinline__ void operator()(AccRef acc, const Unit& u, int wr, int wc, int fr, int fq) const {
;     ...
;                 f32x4 h2v = (f32x4){0.f, 0.f, 0.f, 0.f}, h3v = h2v, h2g = h2v, h3g = h2v;
;                 const int pb = ai * 2 + wr - 1;
;                 if (pb >= 0 && fr == 0) { const LAS float* xp = xch + (pb * 2) * 256 + clb + 4 * n;
;                     h2v = *(const LAS f32x4*)(xp); h3v = *(const LAS f32x4*)(xp + 256); h2g = *(const LAS f32x4*)(xp + 128); h3g = *(const LAS f32x4*)(xp + 256 + 128); }
;                 float o[4][4];
; #pragma unroll
;                 for (int j = 0; j < 4; ++j) {
;                     const float v0 = acc[ai][0][0][n][j], v1 = acc[ai][0][1][n][j], v2 = acc[ai][0][2][n][j], v3 = acc[ai][0][3][n][j];
;                     const float g0 = acc[ai][1][0][n][j], g1 = acc[ai][1][1][n][j], g2 = acc[ai][1][2][n][j], g3 = acc[ai][1][3][n][j];
;                     const float pv3 = dpp_upd<0x111>(h3v[j], v3), pv2 = dpp_upd<0x111>(h2v[j], v2), pg3 = dpp_upd<0x111>(h3g[j], g3), pg2 = dpp_upd<0x111>(h2g[j], g2);
;                     const float hv0 = bvv[j] + w2v[j] * v0 + w1v[j] * pv3 + w0v[j] * pv2, hv1 = bvv[j] + w2v[j] * v1 + w1v[j] * v0 + w0v[j] * pv3;
;                     const float hv2 = bvv[j] + w2v[j] * v2 + w1v[j] * v1 + w0v[j] * v0, hv3 = bvv[j] + w2v[j] * v3 + w1v[j] * v2 + w0v[j] * v1;
;                     const float hg0 = bvg[j] + w2g[j] * g0 + w1g[j] * pg3 + w0g[j] * pg2, hg1 = bvg[j] + w2g[j] * g1 + w1g[j] * g0 + w0g[j] * pg3;
;                     const float hg2 = bvg[j] + w2g[j] * g2 + w1g[j] * g1 + w0g[j] * g0, hg3 = bvg[j] + w2g[j] * g3 + w1g[j] * g2 + w0g[j] * g1;
;                     o[0][j] = hg0 * sigmoidf_(hg0) * hv0; o[1][j] = hg1 * sigmoidf_(hg1) * hv1; o[2][j] = hg2 * sigmoidf_(hg2) * hv2; o[3][j] = hg3 * sigmoidf_(hg3) * hv3; }
; #pragma unroll
;                 for (int m = 0; m < 4; ++m) { u32x2 w; w.x = cvt_pk_bf16(o[m][0], o[m][1]); w.y = cvt_pk_bf16(o[m][2], o[m][3]);
;                     *(u32x2*)(Aout + (size_t)(row0 + ai * 128 + m) * FH + hc0 + 4 * n) = w; } } }
	v_rcp_f32_e32 v133, v133
	v_rcp_f32_e32 v152, v152
	v_rcp_f32_e32 v153, v153
	v_pk_fma_f32 v[142:143], v[150:151], v[170:171], v[174:175]
	v_pk_fma_f32 v[194:195], v[138:139], v[170:171], v[174:175]
	v_pk_fma_f32 v[136:137], v[136:137], v[164:165], v[148:149]
	v_pk_fma_f32 v[134:135], v[138:139], v[166:167], v[142:143]
	v_pk_fma_f32 v[194:195], v[146:147], v[166:167], v[194:195]
	v_pk_fma_f32 v[136:137], v[144:145], v[160:161], v[136:137]
	v_pk_mul_f32 v[128:129], v[128:129], v[140:141]
	v_pk_fma_f32 v[134:135], v[146:147], v[162:163], v[134:135]
	v_pk_mul_f32 v[130:131], v[130:131], v[132:133]
	v_pk_fma_f32 v[158:159], v[158:159], v[162:163], v[194:195]
	v_pk_mul_f32 v[152:153], v[154:155], v[152:153]
	v_pk_mul_f32 v[128:129], v[136:137], v[128:129]
	v_pk_mul_f32 v[130:131], v[134:135], v[130:131]
	v_pk_mul_f32 v[152:153], v[158:159], v[152:153]
	v_cvt_pk_bf16_f32 v251, v128, v129
	v_cvt_pk_bf16_f32 v253, v130, v131
	v_or_b32_e32 v130, 3, v246
	v_cvt_pk_bf16_f32 v255, v152, v153
	v_or_b32_e32 v152, 2, v246
	v_mad_i64_i32 v[130:131], s[42:43], v130, s82, v[206:207]
	v_mad_i64_i32 v[152:153], s[42:43], v152, s82, v[206:207]
	v_lshl_add_u64 v[140:141], v[130:131], 0, v[204:205]
	v_lshl_add_u64 v[152:153], v[152:153], 0, v[204:205]
	v_mov_b32_e32 v193, 0
	v_mov_b64_e32 v[194:195], 0
	v_mov_b64_e32 v[136:137], 0
	v_mov_b64_e32 v[138:139], 0
	v_mov_b64_e32 v[128:129], 0
	v_mov_b64_e32 v[130:131], 0
	v_mov_b64_e32 v[132:133], 0
	v_mov_b64_e32 v[134:135], 0
	s_barrier
	s_and_saveexec_b64 s[42:43], s[30:31]
	s_cbranch_execz .LBB0_1370
	ds_read_b128 v[132:135], v237 offset:2048
	ds_read_b128 v[136:139], v237 offset:2560
	ds_read_b128 v[128:131], v237 offset:3072
	ds_read_b128 v[192:195], v237 offset:3584
.LBB0_1370:
	s_or_b64 exec, exec, s[42:43]
	s_waitcnt lgkmcnt(0)
	v_mov_b32_dpp v192, v72 row_shr:1 row_mask:0xf bank_mask:0xf
	v_mov_b32_dpp v193, v73 row_shr:1 row_mask:0xf bank_mask:0xf
	v_pk_fma_f32 v[142:143], v[88:89], v[184:185], v[188:189]
	v_mov_b32_dpp v136, v64 row_shr:1 row_mask:0xf bank_mask:0xf
	v_mov_b32_dpp v137, v65 row_shr:1 row_mask:0xf bank_mask:0xf
	v_pk_fma_f32 v[142:143], v[180:181], v[192:193], v[142:143]
	v_mov_b32_dpp v128, v84 row_shr:1 row_mask:0xf bank_mask:0xf
	v_pk_fma_f32 v[136:137], v[176:177], v[136:137], v[142:143]
	v_mov_b32_dpp v129, v85 row_shr:1 row_mask:0xf bank_mask:0xf
	v_exp_f32_e32 v142, v136
	v_exp_f32_e32 v143, v137
	v_pk_fma_f32 v[144:145], v[92:93], v[168:169], v[172:173]
	v_mov_b32_dpp v132, v76 row_shr:1 row_mask:0xf bank_mask:0xf
	v_pk_add_f32 v[142:143], v[142:143], 1.0 op_sel_hi:[1,0]
	v_rcp_f32_e32 v142, v142
	v_rcp_f32_e32 v143, v143
	v_mov_b32_dpp v133, v77 row_shr:1 row_mask:0xf bank_mask:0xf
	v_pk_fma_f32 v[144:145], v[164:165], v[128:129], v[144:145]
	v_mov_b32_dpp v194, v74 row_shr:1 row_mask:0xf bank_mask:0xf
	v_pk_fma_f32 v[132:133], v[160:161], v[132:133], v[144:145]
	v_pk_mul_f32 v[136:137], v[136:137], v[142:143]
	v_mov_b32_dpp v195, v75 row_shr:1 row_mask:0xf bank_mask:0xf
	v_pk_mul_f32 v[132:133], v[132:133], v[136:137]
	v_pk_fma_f32 v[136:137], v[90:91], v[186:187], v[190:191]
	v_mov_b32_dpp v138, v66 row_shr:1 row_mask:0xf bank_mask:0xf
	v_mov_b32_dpp v139, v67 row_shr:1 row_mask:0xf bank_mask:0xf
	v_pk_fma_f32 v[136:137], v[182:183], v[194:195], v[136:137]
	v_mov_b32_dpp v130, v86 row_shr:1 row_mask:0xf bank_mask:0xf
	v_pk_fma_f32 v[136:137], v[178:179], v[138:139], v[136:137]
	v_mov_b32_dpp v131, v87 row_shr:1 row_mask:0xf bank_mask:0xf
	v_exp_f32_e32 v139, v136
	v_exp_f32_e32 v142, v137
	v_cvt_pk_bf16_f32 v144, v132, v133
	v_add_f32_e32 v132, 1.0, v139
	v_rcp_f32_e32 v132, v132
	v_add_f32_e32 v133, 1.0, v142
	v_rcp_f32_e32 v133, v133
	v_pk_fma_f32 v[142:143], v[94:95], v[170:171], v[174:175]
	v_mov_b32_dpp v134, v78 row_shr:1 row_mask:0xf bank_mask:0xf
	v_mov_b32_dpp v135, v79 row_shr:1 row_mask:0xf bank_mask:0xf
	v_pk_mul_f32 v[132:133], v[136:137], v[132:133]
	v_pk_fma_f32 v[136:137], v[68:69], v[184:185], v[188:189]
	v_pk_fma_f32 v[142:143], v[166:167], v[130:131], v[142:143]
	v_pk_fma_f32 v[136:137], v[88:89], v[180:181], v[136:137]
	v_pk_fma_f32 v[134:135], v[162:163], v[134:135], v[142:143]
	v_pk_fma_f32 v[136:137], v[176:177], v[192:193], v[136:137]
	v_add_u32_e32 v146, 0x80, v246
	v_exp_f32_e32 v142, v136
	v_exp_f32_e32 v143, v137
	v_pk_mul_f32 v[132:133], v[134:135], v[132:133]
	v_mov_b64_e32 v[134:135], s[60:61]
	v_cvt_pk_bf16_f32 v145, v132, v133
	v_mad_i64_i32 v[132:133], s[42:43], v146, s82, v[134:135]
	v_lshl_add_u64 v[132:133], v[132:133], 0, v[204:205]
	v_add_f32_e32 v138, 1.0, v142
	v_add_f32_e32 v139, 1.0, v143
	v_rcp_f32_e32 v138, v138
	v_rcp_f32_e32 v139, v139
	v_pk_fma_f32 v[142:143], v[80:81], v[168:169], v[172:173]
	v_pk_fma_f32 v[72:73], v[72:73], v[184:185], v[188:189]
	v_pk_fma_f32 v[142:143], v[92:93], v[164:165], v[142:143]
	v_pk_mul_f32 v[136:137], v[136:137], v[138:139]
	v_pk_fma_f32 v[128:129], v[160:161], v[128:129], v[142:143]
	v_pk_fma_f32 v[84:85], v[84:85], v[168:169], v[172:173]
	v_pk_mul_f32 v[128:129], v[128:129], v[136:137]
	v_pk_fma_f32 v[136:137], v[70:71], v[186:187], v[190:191]
	s_nop 0
	v_pk_fma_f32 v[136:137], v[90:91], v[182:183], v[136:137]
	s_nop 0
	v_pk_fma_f32 v[136:137], v[178:179], v[194:195], v[136:137]
	s_nop 0
	v_exp_f32_e32 v139, v136
	v_exp_f32_e32 v142, v137
	v_cvt_pk_bf16_f32 v138, v128, v129
	v_add_f32_e32 v128, 1.0, v139
	v_rcp_f32_e32 v128, v128
	v_add_f32_e32 v129, 1.0, v142
	v_rcp_f32_e32 v129, v129
	v_pk_fma_f32 v[142:143], v[82:83], v[170:171], v[174:175]
	v_pk_mul_f32 v[128:129], v[136:137], v[128:129]
	v_pk_fma_f32 v[142:143], v[94:95], v[166:167], v[142:143]
	v_pk_fma_f32 v[136:137], v[76:77], v[168:169], v[172:173]
; #define LAS __attribute__((address_space(3)))
; __device__ __forceinline__ float sigmoidf_(float x) { return __builtin_amdgcn_rcpf(1.0f + __expf(-x)); }
;     __device__ __forceinline__ void operator()(AccRef acc, const Unit& u, int wr, int wc, int fr, int fq) const {
;     ...
;                 f32x4 h2v = (f32x4){0.f, 0.f, 0.f, 0.f}, h3v = h2v, h2g = h2v, h3g = h2v;
;                 const int pb = ai * 2 + wr - 1;
;                 if (pb >= 0 && fr == 0) { const LAS float* xp = xch + (pb * 2) * 256 + clb + 4 * n;
;                     h2v = *(const LAS f32x4*)(xp); h3v = *(const LAS f32x4*)(xp + 256); h2g = *(const LAS f32x4*)(xp + 128); h3g = *(const LAS f32x4*)(xp + 256 + 128); }
;                 float o[4][4];
; #pragma unroll
;                 for (int j = 0; j < 4; ++j) {
;                     const float v0 = acc[ai][0][0][n][j], v1 = acc[ai][0][1][n][j], v2 = acc[ai][0][2][n][j], v3 = acc[ai][0][3][n][j];
;                     const float g0 = acc[ai][1][0][n][j], g1 = acc[ai][1][1][n][j], g2 = acc[ai][1][2][n][j], g3 = acc[ai][1][3][n][j];
;                     const float pv3 = dpp_upd<0x111>(h3v[j], v3), pv2 = dpp_upd<0x111>(h2v[j], v2), pg3 = dpp_upd<0x111>(h3g[j], g3), pg2 = dpp_upd<0x111>(h2g[j], g2);
;                     const float hv0 = bvv[j] + w2v[j] * v0 + w1v[j] * pv3 + w0v[j] * pv2, hv1 = bvv[j] + w2v[j] * v1 + w1v[j] * v0 + w0v[j] * pv3;
;                     const float hv2 = bvv[j] + w2v[j] * v2 + w1v[j] * v1 + w0v[j] * v0, hv3 = bvv[j] + w2v[j] * v3 + w1v[j] * v2 + w0v[j] * v1;
;                     const float hg0 = bvg[j] + w2g[j] * g0 + w1g[j] * pg3 + w0g[j] * pg2, hg1 = bvg[j] + w2g[j] * g1 + w1g[j] * g0 + w0g[j] * pg3;
;                     const float hg2 = bvg[j] + w2g[j] * g2 + w1g[j] * g1 + w0g[j] * g0, hg3 = bvg[j] + w2g[j] * g3 + w1g[j] * g2 + w0g[j] * g1;
;                     o[0][j] = hg0 * sigmoidf_(hg0) * hv0; o[1][j] = hg1 * sigmoidf_(hg1) * hv1; o[2][j] = hg2 * sigmoidf_(hg2) * hv2; o[3][j] = hg3 * sigmoidf_(hg3) * hv3; }
; #pragma unroll
;                 for (int m = 0; m < 4; ++m) { u32x2 w; w.x = cvt_pk_bf16(o[m][0], o[m][1]); w.y = cvt_pk_bf16(o[m][2], o[m][3]);
;                     *(u32x2*)(Aout + (size_t)(row0 + ai * 128 + m) * FH + hc0 + 4 * n) = w; } } }
	v_pk_fma_f32 v[130:131], v[162:163], v[130:131], v[142:143]
	v_pk_fma_f32 v[136:137], v[80:81], v[164:165], v[136:137]
	v_pk_mul_f32 v[128:129], v[130:131], v[128:129]
	v_pk_fma_f32 v[130:131], v[64:65], v[184:185], v[188:189]
	v_pk_fma_f32 v[64:65], v[64:65], v[180:181], v[72:73]
	v_pk_fma_f32 v[130:131], v[68:69], v[180:181], v[130:131]
	v_pk_fma_f32 v[64:65], v[68:69], v[176:177], v[64:65]
	v_pk_fma_f32 v[88:89], v[88:89], v[176:177], v[130:131]
	v_pk_fma_f32 v[92:93], v[92:93], v[160:161], v[136:137]
	v_exp_f32_e32 v130, v88
	v_exp_f32_e32 v131, v89
	v_exp_f32_e32 v72, v64
	v_pk_add_f32 v[130:131], v[130:131], 1.0 op_sel_hi:[1,0]
	v_rcp_f32_e32 v130, v130
	v_rcp_f32_e32 v131, v131
	v_pk_fma_f32 v[68:69], v[74:75], v[186:187], v[190:191]
	v_exp_f32_e32 v73, v65
	v_pk_mul_f32 v[88:89], v[88:89], v[130:131]
	v_pk_mul_f32 v[88:89], v[92:93], v[88:89]
	v_pk_fma_f32 v[92:93], v[66:67], v[186:187], v[190:191]
	v_pk_fma_f32 v[66:67], v[66:67], v[182:183], v[68:69]
	v_pk_fma_f32 v[92:93], v[70:71], v[182:183], v[92:93]
	v_pk_fma_f32 v[66:67], v[70:71], v[178:179], v[66:67]
	v_pk_fma_f32 v[90:91], v[90:91], v[178:179], v[92:93]
	v_exp_f32_e32 v93, v90
	v_exp_f32_e32 v68, v66
	v_exp_f32_e32 v69, v67
	v_exp_f32_e32 v130, v91
	v_pk_add_f32 v[72:73], v[72:73], 1.0 op_sel_hi:[1,0]
	v_pk_add_f32 v[68:69], v[68:69], 1.0 op_sel_hi:[1,0]
	v_cvt_pk_bf16_f32 v198, v88, v89
	v_add_f32_e32 v88, 1.0, v93
	v_add_f32_e32 v89, 1.0, v130
	v_rcp_f32_e32 v72, v72
	v_rcp_f32_e32 v73, v73
	v_rcp_f32_e32 v68, v68
	v_rcp_f32_e32 v69, v69
	v_rcp_f32_e32 v88, v88
	v_rcp_f32_e32 v89, v89
	v_pk_fma_f32 v[74:75], v[86:87], v[170:171], v[174:175]
	v_pk_fma_f32 v[130:131], v[78:79], v[170:171], v[174:175]
	v_pk_fma_f32 v[76:77], v[76:77], v[164:165], v[84:85]
	v_pk_fma_f32 v[70:71], v[78:79], v[166:167], v[74:75]
	v_pk_fma_f32 v[130:131], v[82:83], v[166:167], v[130:131]
	v_pk_fma_f32 v[76:77], v[80:81], v[160:161], v[76:77]
	v_pk_mul_f32 v[64:65], v[64:65], v[72:73]
	v_pk_fma_f32 v[70:71], v[82:83], v[162:163], v[70:71]
	v_pk_mul_f32 v[66:67], v[66:67], v[68:69]
	v_pk_fma_f32 v[94:95], v[94:95], v[162:163], v[130:131]
	v_pk_mul_f32 v[88:89], v[90:91], v[88:89]
	v_pk_mul_f32 v[64:65], v[76:77], v[64:65]
	v_pk_mul_f32 v[66:67], v[70:71], v[66:67]
	v_pk_mul_f32 v[88:89], v[94:95], v[88:89]
	v_cvt_pk_bf16_f32 v148, v64, v65
	v_cvt_pk_bf16_f32 v149, v66, v67
	v_add_u32_e32 v66, 0x83, v246
	v_cvt_pk_bf16_f32 v155, v128, v129
	v_add_u32_e32 v128, 0x81, v246
	v_cvt_pk_bf16_f32 v199, v88, v89
	v_add_u32_e32 v88, 0x82, v246
	v_mad_i64_i32 v[66:67], s[42:43], v66, s82, v[134:135]
	v_mad_i64_i32 v[128:129], s[42:43], v128, s82, v[134:135]
	v_mad_i64_i32 v[88:89], s[42:43], v88, s82, v[134:135]
	v_lshl_add_u64 v[82:83], v[66:67], 0, v[204:205]
	v_lshl_add_u64 v[128:129], v[128:129], 0, v[204:205]
	v_lshl_add_u64 v[88:89], v[88:89], 0, v[204:205]
	v_mov_b32_e32 v64, 0
	v_mov_b64_e32 v[70:71], 0
	v_mov_b64_e32 v[72:73], 0
	v_mov_b64_e32 v[78:79], 0
	v_mov_b64_e32 v[80:81], 0
	v_mov_b64_e32 v[66:67], 0
	v_mov_b64_e32 v[68:69], 0
	v_mov_b64_e32 v[74:75], 0
	v_mov_b64_e32 v[76:77], 0
	v_mov_b32_e32 v154, v138
	s_barrier
	s_and_saveexec_b64 s[42:43], s[28:29]
	s_cbranch_execz .LBB0_1372
	ds_read_b128 v[74:77], v242
	ds_read_b128 v[66:69], v241
	ds_read_b128 v[78:81], v240
	ds_read_b128 v[70:73], v239
; #define LAS __attribute__((address_space(3)))
; __device__ __forceinline__ float sigmoidf_(float x) { return __builtin_amdgcn_rcpf(1.0f + __expf(-x)); }
;     __device__ __forceinline__ void operator()(AccRef acc, const Unit& u, int wr, int wc, int fr, int fq) const {
;     ...
;                 f32x4 h2v = (f32x4){0.f, 0.f, 0.f, 0.f}, h3v = h2v, h2g = h2v, h3g = h2v;
;                 const int pb = ai * 2 + wr - 1;
;                 if (pb >= 0 && fr == 0) { const LAS float* xp = xch + (pb * 2) * 256 + clb + 4 * n;
;                     h2v = *(const LAS f32x4*)(xp); h3v = *(const LAS f32x4*)(xp + 256); h2g = *(const LAS f32x4*)(xp + 128); h3g = *(const LAS f32x4*)(xp + 256 + 128); }
;                 float o[4][4];
; #pragma unroll
;                 for (int j = 0; j < 4; ++j) {
;                     const float v0 = acc[ai][0][0][n][j], v1 = acc[ai][0][1][n][j], v2 = acc[ai][0][2][n][j], v3 = acc[ai][0][3][n][j];
;                     const float g0 = acc[ai][1][0][n][j], g1 = acc[ai][1][1][n][j], g2 = acc[ai][1][2][n][j], g3 = acc[ai][1][3][n][j];
;                     const float pv3 = dpp_upd<0x111>(h3v[j], v3), pv2 = dpp_upd<0x111>(h2v[j], v2), pg3 = dpp_upd<0x111>(h3g[j], g3), pg2 = dpp_upd<0x111>(h2g[j], g2);
;                     const float hv0 = bvv[j] + w2v[j] * v0 + w1v[j] * pv3 + w0v[j] * pv2, hv1 = bvv[j] + w2v[j] * v1 + w1v[j] * v0 + w0v[j] * pv3;
;                     const float hv2 = bvv[j] + w2v[j] * v2 + w1v[j] * v1 + w0v[j] * v0, hv3 = bvv[j] + w2v[j] * v3 + w1v[j] * v2 + w0v[j] * v1;
;                     const float hg0 = bvg[j] + w2g[j] * g0 + w1g[j] * pg3 + w0g[j] * pg2, hg1 = bvg[j] + w2g[j] * g1 + w1g[j] * g0 + w0g[j] * pg3;
;                     const float hg2 = bvg[j] + w2g[j] * g2 + w1g[j] * g1 + w0g[j] * g0, hg3 = bvg[j] + w2g[j] * g3 + w1g[j] * g2 + w0g[j] * g1;
;                     o[0][j] = hg0 * sigmoidf_(hg0) * hv0; o[1][j] = hg1 * sigmoidf_(hg1) * hv1; o[2][j] = hg2 * sigmoidf_(hg2) * hv2; o[3][j] = hg3 * sigmoidf_(hg3) * hv3; }
; #pragma unroll
;                 for (int m = 0; m < 4; ++m) { u32x2 w; w.x = cvt_pk_bf16(o[m][0], o[m][1]); w.y = cvt_pk_bf16(o[m][2], o[m][3]);
;                     *(u32x2*)(Aout + (size_t)(row0 + ai * 128 + m) * FH + hc0 + 4 * n) = w; } } }
.LBB0_1372:
	s_or_b64 exec, exec, s[42:43]
	s_waitcnt lgkmcnt(0)
	v_mov_b32_dpp v70, v44 row_shr:1 row_mask:0xf bank_mask:0xf
	v_mov_b32_dpp v71, v45 row_shr:1 row_mask:0xf bank_mask:0xf
	s_waitcnt vmcnt(0)
	v_pk_fma_f32 v[84:85], v[56:57], v[120:121], v[124:125]
	v_mov_b32_dpp v78, v32 row_shr:1 row_mask:0xf bank_mask:0xf
	v_mov_b32_dpp v79, v33 row_shr:1 row_mask:0xf bank_mask:0xf
	v_pk_fma_f32 v[84:85], v[116:117], v[70:71], v[84:85]
	v_mov_b32_dpp v66, v52 row_shr:1 row_mask:0xf bank_mask:0xf
	v_pk_fma_f32 v[78:79], v[112:113], v[78:79], v[84:85]
	v_mov_b32_dpp v67, v53 row_shr:1 row_mask:0xf bank_mask:0xf
	v_exp_f32_e32 v84, v78
	v_exp_f32_e32 v85, v79
	v_pk_fma_f32 v[86:87], v[60:61], v[104:105], v[108:109]
	v_pk_add_f32 v[84:85], v[84:85], 1.0 op_sel_hi:[1,0]
	v_rcp_f32_e32 v84, v84
	v_rcp_f32_e32 v85, v85
	v_mov_b32_dpp v74, v40 row_shr:1 row_mask:0xf bank_mask:0xf
	v_mov_b32_dpp v75, v41 row_shr:1 row_mask:0xf bank_mask:0xf
	v_pk_fma_f32 v[86:87], v[100:101], v[66:67], v[86:87]
	v_pk_mul_f32 v[78:79], v[78:79], v[84:85]
	v_pk_fma_f32 v[74:75], v[96:97], v[74:75], v[86:87]
	v_mov_b32_dpp v72, v46 row_shr:1 row_mask:0xf bank_mask:0xf
	v_mov_b32_dpp v73, v47 row_shr:1 row_mask:0xf bank_mask:0xf
	v_pk_mul_f32 v[74:75], v[74:75], v[78:79]
	v_pk_fma_f32 v[78:79], v[58:59], v[122:123], v[126:127]
	v_mov_b32_dpp v80, v34 row_shr:1 row_mask:0xf bank_mask:0xf
	v_mov_b32_dpp v81, v35 row_shr:1 row_mask:0xf bank_mask:0xf
	v_pk_fma_f32 v[78:79], v[118:119], v[72:73], v[78:79]
	v_mov_b32_dpp v68, v54 row_shr:1 row_mask:0xf bank_mask:0xf
	v_pk_fma_f32 v[78:79], v[114:115], v[80:81], v[78:79]
	v_mov_b32_dpp v69, v55 row_shr:1 row_mask:0xf bank_mask:0xf
	v_exp_f32_e32 v80, v78
	v_exp_f32_e32 v81, v79
	v_pk_fma_f32 v[84:85], v[62:63], v[106:107], v[110:111]
	v_pk_add_f32 v[80:81], v[80:81], 1.0 op_sel_hi:[1,0]
	v_rcp_f32_e32 v80, v80
	v_rcp_f32_e32 v81, v81
	v_mov_b32_dpp v76, v42 row_shr:1 row_mask:0xf bank_mask:0xf
	v_mov_b32_dpp v77, v43 row_shr:1 row_mask:0xf bank_mask:0xf
	v_pk_fma_f32 v[84:85], v[102:103], v[68:69], v[84:85]
	v_pk_mul_f32 v[78:79], v[78:79], v[80:81]
	v_pk_fma_f32 v[76:77], v[98:99], v[76:77], v[84:85]
	v_cvt_pk_bf16_f32 v92, v74, v75
	v_pk_mul_f32 v[76:77], v[76:77], v[78:79]
	v_pk_fma_f32 v[44:45], v[44:45], v[120:121], v[124:125]
	v_cvt_pk_bf16_f32 v93, v76, v77
	v_pk_fma_f32 v[76:77], v[36:37], v[120:121], v[124:125]
	v_mov_b32_e32 v90, v247
	v_mov_b32_e32 v91, v248
	global_store_dwordx4 v[202:203], v[90:93], off
	v_pk_fma_f32 v[76:77], v[56:57], v[116:117], v[76:77]
	v_pk_fma_f32 v[52:53], v[52:53], v[104:105], v[108:109]
	v_pk_fma_f32 v[70:71], v[112:113], v[70:71], v[76:77]
	s_nop 0
	v_exp_f32_e32 v74, v70
	v_exp_f32_e32 v75, v71
	s_nop 0
	v_pk_add_f32 v[74:75], v[74:75], 1.0 op_sel_hi:[1,0]
	v_rcp_f32_e32 v74, v74
	v_rcp_f32_e32 v75, v75
	v_pk_fma_f32 v[76:77], v[48:49], v[104:105], v[108:109]
	v_pk_mul_f32 v[70:71], v[70:71], v[74:75]
	v_pk_fma_f32 v[76:77], v[60:61], v[100:101], v[76:77]
	v_pk_fma_f32 v[74:75], v[50:51], v[106:107], v[110:111]
	v_pk_fma_f32 v[66:67], v[96:97], v[66:67], v[76:77]
	v_pk_fma_f32 v[74:75], v[62:63], v[102:103], v[74:75]
	v_pk_mul_f32 v[66:67], v[66:67], v[70:71]
	v_pk_fma_f32 v[70:71], v[38:39], v[122:123], v[126:127]
	v_pk_fma_f32 v[68:69], v[98:99], v[68:69], v[74:75]
	v_pk_fma_f32 v[70:71], v[58:59], v[118:119], v[70:71]
	v_cvt_pk_bf16_f32 v136, v66, v67
	v_pk_fma_f32 v[70:71], v[114:115], v[72:73], v[70:71]
	s_nop 0
	v_exp_f32_e32 v72, v70
	v_exp_f32_e32 v73, v71
	s_nop 0
	v_pk_add_f32 v[72:73], v[72:73], 1.0 op_sel_hi:[1,0]
	v_rcp_f32_e32 v72, v72
	v_rcp_f32_e32 v73, v73
	s_nop 0
	v_pk_mul_f32 v[70:71], v[70:71], v[72:73]
	s_nop 0
	v_pk_mul_f32 v[68:69], v[68:69], v[70:71]
	s_nop 0
	v_cvt_pk_bf16_f32 v137, v68, v69
	v_pk_fma_f32 v[68:69], v[32:33], v[120:121], v[124:125]
	v_mov_b32_e32 v134, v249
	v_mov_b32_e32 v135, v250
	global_store_dwordx4 v[196:197], v[134:137], off
	v_pk_fma_f32 v[68:69], v[36:37], v[116:117], v[68:69]
	v_pk_fma_f32 v[32:33], v[32:33], v[116:117], v[44:45]
	v_pk_fma_f32 v[56:57], v[56:57], v[112:113], v[68:69]
	v_pk_fma_f32 v[32:33], v[36:37], v[112:113], v[32:33]
	v_exp_f32_e32 v66, v56
	v_exp_f32_e32 v67, v57
	s_nop 0
	v_pk_add_f32 v[66:67], v[66:67], 1.0 op_sel_hi:[1,0]
	v_rcp_f32_e32 v66, v66
	v_rcp_f32_e32 v67, v67
	v_pk_fma_f32 v[68:69], v[40:41], v[104:105], v[108:109]
	v_exp_f32_e32 v44, v32
	v_pk_fma_f32 v[68:69], v[48:49], v[100:101], v[68:69]
	v_pk_mul_f32 v[56:57], v[56:57], v[66:67]
	v_pk_fma_f32 v[60:61], v[60:61], v[96:97], v[68:69]
	v_pk_fma_f32 v[36:37], v[46:47], v[122:123], v[126:127]
	v_pk_mul_f32 v[56:57], v[60:61], v[56:57]
	v_pk_fma_f32 v[60:61], v[34:35], v[122:123], v[126:127]
	v_pk_fma_f32 v[34:35], v[34:35], v[118:119], v[36:37]
	v_pk_fma_f32 v[60:61], v[38:39], v[118:119], v[60:61]
	v_pk_fma_f32 v[34:35], v[38:39], v[114:115], v[34:35]
	v_pk_fma_f32 v[58:59], v[58:59], v[114:115], v[60:61]
	v_exp_f32_e32 v60, v58
	v_exp_f32_e32 v45, v33
	v_exp_f32_e32 v36, v34
	v_exp_f32_e32 v37, v35
	v_exp_f32_e32 v61, v59
	v_cvt_pk_bf16_f32 v164, v56, v57
	v_pk_add_f32 v[44:45], v[44:45], 1.0 op_sel_hi:[1,0]
	v_pk_add_f32 v[36:37], v[36:37], 1.0 op_sel_hi:[1,0]
	v_pk_add_f32 v[60:61], v[60:61], 1.0 op_sel_hi:[1,0]
	v_rcp_f32_e32 v44, v44
	v_rcp_f32_e32 v45, v45
	v_rcp_f32_e32 v36, v36
	v_rcp_f32_e32 v37, v37
	v_rcp_f32_e32 v60, v60
	v_rcp_f32_e32 v61, v61
	v_pk_fma_f32 v[46:47], v[54:55], v[106:107], v[110:111]
	v_pk_fma_f32 v[66:67], v[42:43], v[106:107], v[110:111]
	v_pk_fma_f32 v[40:41], v[40:41], v[100:101], v[52:53]
	v_pk_fma_f32 v[38:39], v[42:43], v[102:103], v[46:47]
	v_pk_fma_f32 v[66:67], v[50:51], v[102:103], v[66:67]
	v_pk_fma_f32 v[40:41], v[48:49], v[96:97], v[40:41]
	v_pk_mul_f32 v[32:33], v[32:33], v[44:45]
	v_pk_fma_f32 v[38:39], v[50:51], v[98:99], v[38:39]
	v_pk_mul_f32 v[34:35], v[34:35], v[36:37]
	v_pk_fma_f32 v[62:63], v[62:63], v[98:99], v[66:67]
	v_pk_mul_f32 v[58:59], v[58:59], v[60:61]
	v_pk_mul_f32 v[32:33], v[40:41], v[32:33]
	v_pk_mul_f32 v[34:35], v[38:39], v[34:35]
	v_pk_mul_f32 v[58:59], v[62:63], v[58:59]
	v_cvt_pk_bf16_f32 v160, v32, v33
	v_cvt_pk_bf16_f32 v161, v34, v35
	v_cvt_pk_bf16_f32 v57, v58, v59
	v_mov_b32_e32 v158, v251
	v_mov_b32_e32 v159, v253
	global_store_dwordx4 v[140:141], v[158:161], off
	v_mov_b32_e32 v65, 0
	v_mov_b64_e32 v[66:67], 0
	v_mov_b64_e32 v[40:41], 0
	v_mov_b64_e32 v[42:43], 0
	v_mov_b64_e32 v[32:33], 0
	v_mov_b64_e32 v[34:35], 0
	v_mov_b64_e32 v[36:37], 0
	v_mov_b64_e32 v[38:39], 0
	v_mov_b32_e32 v162, v254
	v_mov_b32_e32 v163, v255
	v_mov_b32_e32 v165, v57
	global_store_dwordx4 v[152:153], v[162:165], off
	s_barrier
	s_and_saveexec_b64 s[42:43], s[30:31]
	s_cbranch_execz .LBB0_1355
	ds_read_b128 v[36:39], v237 offset:2064
	ds_read_b128 v[40:43], v237 offset:2576
	ds_read_b128 v[32:35], v237 offset:3088
	ds_read_b128 v[64:67], v237 offset:3600
	s_branch .LBB0_1355

; #define LAS __attribute__((address_space(3)))
; __device__ __forceinline__ float sigmoidf_(float x) { return __builtin_amdgcn_rcpf(1.0f + __expf(-x)); }
;     __device__ __forceinline__ void operator()(AccRef acc, const Unit& u, int wr, int wc, int fr, int fq) const {
;     ...
;                 f32x4 h2v = (f32x4){0.f, 0.f, 0.f, 0.f}, h3v = h2v, h2g = h2v, h3g = h2v;
;                 const int pb = ai * 2 + wr - 1;
;                 if (pb >= 0 && fr == 0) { const LAS float* xp = xch + (pb * 2) * 256 + clb + 4 * n;
;                     h2v = *(const LAS f32x4*)(xp); h3v = *(const LAS f32x4*)(xp + 256); h2g = *(const LAS f32x4*)(xp + 128); h3g = *(const LAS f32x4*)(xp + 256 + 128); }
;                 float o[4][4];
; #pragma unroll
;                 for (int j = 0; j < 4; ++j) {
;                     const float v0 = acc[ai][0][0][n][j], v1 = acc[ai][0][1][n][j], v2 = acc[ai][0][2][n][j], v3 = acc[ai][0][3][n][j];
;                     const float g0 = acc[ai][1][0][n][j], g1 = acc[ai][1][1][n][j], g2 = acc[ai][1][2][n][j], g3 = acc[ai][1][3][n][j];
;                     const float pv3 = dpp_upd<0x111>(h3v[j], v3), pv2 = dpp_upd<0x111>(h2v[j], v2), pg3 = dpp_upd<0x111>(h3g[j], g3), pg2 = dpp_upd<0x111>(h2g[j], g2);
;                     const float hv0 = bvv[j] + w2v[j] * v0 + w1v[j] * pv3 + w0v[j] * pv2, hv1 = bvv[j] + w2v[j] * v1 + w1v[j] * v0 + w0v[j] * pv3;
;                     const float hv2 = bvv[j] + w2v[j] * v2 + w1v[j] * v1 + w0v[j] * v0, hv3 = bvv[j] + w2v[j] * v3 + w1v[j] * v2 + w0v[j] * v1;
;                     const float hg0 = bvg[j] + w2g[j] * g0 + w1g[j] * pg3 + w0g[j] * pg2, hg1 = bvg[j] + w2g[j] * g1 + w1g[j] * g0 + w0g[j] * pg3;
;                     const float hg2 = bvg[j] + w2g[j] * g2 + w1g[j] * g1 + w0g[j] * g0, hg3 = bvg[j] + w2g[j] * g3 + w1g[j] * g2 + w0g[j] * g1;
;                     o[0][j] = hg0 * sigmoidf_(hg0) * hv0; o[1][j] = hg1 * sigmoidf_(hg1) * hv1; o[2][j] = hg2 * sigmoidf_(hg2) * hv2; o[3][j] = hg3 * sigmoidf_(hg3) * hv3; }
; #pragma unroll
;                 for (int m = 0; m < 4; ++m) { u32x2 w; w.x = cvt_pk_bf16(o[m][0], o[m][1]); w.y = cvt_pk_bf16(o[m][2], o[m][3]);
;                     *(u32x2*)(Aout + (size_t)(row0 + ai * 128 + m) * FH + hc0 + 4 * n) = w; } } }
.LBB0_1947:
	s_or_b64 exec, exec, s[40:41]
	v_pk_fma_f32 v[246:247], v[152:153], v[184:185], v[188:189]
	v_mov_b32_dpp v206, v128 row_shr:1 row_mask:0xf bank_mask:0xf
	v_mov_b32_dpp v207, v129 row_shr:1 row_mask:0xf bank_mask:0xf
	v_pk_fma_f32 v[246:247], v[180:181], v[198:199], v[246:247]
	v_mov_b32_dpp v194, v148 row_shr:1 row_mask:0xf bank_mask:0xf
	v_pk_fma_f32 v[206:207], v[176:177], v[206:207], v[246:247]
	v_mov_b32_dpp v195, v149 row_shr:1 row_mask:0xf bank_mask:0xf
	v_exp_f32_e32 v246, v206
	v_exp_f32_e32 v247, v207
	v_pk_fma_f32 v[248:249], v[156:157], v[168:169], v[172:173]
	v_pk_add_f32 v[246:247], v[246:247], 1.0 op_sel_hi:[1,0]
	v_rcp_f32_e32 v246, v246
	v_rcp_f32_e32 v247, v247
	v_mov_b32_dpp v202, v136 row_shr:1 row_mask:0xf bank_mask:0xf
	v_mov_b32_dpp v203, v137 row_shr:1 row_mask:0xf bank_mask:0xf
	v_pk_fma_f32 v[248:249], v[164:165], v[194:195], v[248:249]
	v_pk_mul_f32 v[206:207], v[206:207], v[246:247]
	v_pk_fma_f32 v[202:203], v[160:161], v[202:203], v[248:249]
	v_mov_b32_dpp v200, v142 row_shr:1 row_mask:0xf bank_mask:0xf
	v_mov_b32_dpp v201, v143 row_shr:1 row_mask:0xf bank_mask:0xf
	v_pk_mul_f32 v[202:203], v[202:203], v[206:207]
	v_pk_fma_f32 v[206:207], v[154:155], v[186:187], v[190:191]
	v_mov_b32_dpp v208, v130 row_shr:1 row_mask:0xf bank_mask:0xf
	v_mov_b32_dpp v209, v131 row_shr:1 row_mask:0xf bank_mask:0xf
	v_pk_fma_f32 v[206:207], v[182:183], v[200:201], v[206:207]
	v_mov_b32_dpp v196, v150 row_shr:1 row_mask:0xf bank_mask:0xf
	v_pk_fma_f32 v[206:207], v[178:179], v[208:209], v[206:207]
	v_mov_b32_dpp v197, v151 row_shr:1 row_mask:0xf bank_mask:0xf
	v_exp_f32_e32 v193, v206
	v_exp_f32_e32 v209, v207
	v_cvt_pk_bf16_f32 v208, v202, v203
	v_add_f32_e32 v193, 1.0, v193
	v_rcp_f32_e32 v202, v193
	v_add_f32_e32 v193, 1.0, v209
	v_rcp_f32_e32 v203, v193
	v_pk_fma_f32 v[246:247], v[158:159], v[170:171], v[174:175]
	v_mov_b32_dpp v204, v138 row_shr:1 row_mask:0xf bank_mask:0xf
	v_mov_b32_dpp v205, v139 row_shr:1 row_mask:0xf bank_mask:0xf
	v_pk_fma_f32 v[246:247], v[166:167], v[196:197], v[246:247]
	v_pk_mul_f32 v[202:203], v[206:207], v[202:203]
	v_pk_fma_f32 v[204:205], v[162:163], v[204:205], v[246:247]
	v_lshl_add_u32 v245, s34, 8, v235
	v_pk_mul_f32 v[202:203], v[204:205], v[202:203]
	v_lshlrev_b64 v[204:205], 1, v[232:233]
	v_pk_fma_f32 v[232:233], v[132:133], v[184:185], v[188:189]
	v_mov_b64_e32 v[206:207], s[60:61]
	v_pk_fma_f32 v[232:233], v[152:153], v[180:181], v[232:233]
	v_cvt_pk_bf16_f32 v247, v202, v203
	v_pk_fma_f32 v[198:199], v[176:177], v[198:199], v[232:233]
	v_mad_i64_i32 v[202:203], s[34:35], v245, s63, v[206:207]
	v_exp_f32_e32 v193, v198
	v_exp_f32_e32 v232, v199
	v_lshl_add_u64 v[202:203], v[202:203], 0, v[204:205]
	v_add_f32_e32 v193, 1.0, v193
	v_mov_b32_e32 v246, v208
	v_rcp_f32_e32 v208, v193
	v_add_f32_e32 v193, 1.0, v232
	v_rcp_f32_e32 v209, v193
	v_pk_fma_f32 v[232:233], v[144:145], v[168:169], v[172:173]
	v_pk_fma_f32 v[140:141], v[140:141], v[184:185], v[188:189]
	v_pk_fma_f32 v[232:233], v[156:157], v[164:165], v[232:233]
	v_pk_mul_f32 v[198:199], v[198:199], v[208:209]
	v_pk_fma_f32 v[194:195], v[160:161], v[194:195], v[232:233]
	v_pk_fma_f32 v[208:209], v[146:147], v[170:171], v[174:175]
	v_pk_mul_f32 v[194:195], v[194:195], v[198:199]
	v_pk_fma_f32 v[198:199], v[134:135], v[186:187], v[190:191]
	v_pk_fma_f32 v[208:209], v[158:159], v[166:167], v[208:209]
	v_pk_fma_f32 v[198:199], v[154:155], v[182:183], v[198:199]
	v_pk_fma_f32 v[196:197], v[162:163], v[196:197], v[208:209]
	v_pk_fma_f32 v[198:199], v[178:179], v[200:201], v[198:199]
	v_cvt_pk_bf16_f32 v248, v194, v195
	v_exp_f32_e32 v200, v198
	v_exp_f32_e32 v201, v199
	v_pk_fma_f32 v[148:149], v[148:149], v[168:169], v[172:173]
	v_pk_add_f32 v[200:201], v[200:201], 1.0 op_sel_hi:[1,0]
	v_rcp_f32_e32 v200, v200
	v_rcp_f32_e32 v201, v201
	v_or_b32_e32 v193, 1, v245
	v_pk_mul_f32 v[198:199], v[198:199], v[200:201]
	s_nop 0
	v_pk_mul_f32 v[196:197], v[196:197], v[198:199]
	v_pk_fma_f32 v[198:199], v[128:129], v[184:185], v[188:189]
	v_cvt_pk_bf16_f32 v249, v196, v197
	v_pk_fma_f32 v[198:199], v[132:133], v[180:181], v[198:199]
	v_mad_i64_i32 v[196:197], s[34:35], v193, s63, v[206:207]
	v_pk_fma_f32 v[152:153], v[152:153], v[176:177], v[198:199]
	v_lshl_add_u64 v[196:197], v[196:197], 0, v[204:205]
	v_exp_f32_e32 v193, v152
	v_exp_f32_e32 v198, v153
	v_add_f32_e32 v193, 1.0, v193
	v_rcp_f32_e32 v194, v193
	v_add_f32_e32 v193, 1.0, v198
	v_rcp_f32_e32 v195, v193
	v_pk_fma_f32 v[198:199], v[136:137], v[168:169], v[172:173]
	v_pk_fma_f32 v[128:129], v[128:129], v[180:181], v[140:141]
	v_pk_fma_f32 v[198:199], v[144:145], v[164:165], v[198:199]
	v_pk_fma_f32 v[128:129], v[132:133], v[176:177], v[128:129]
	v_pk_fma_f32 v[156:157], v[156:157], v[160:161], v[198:199]
	v_pk_mul_f32 v[152:153], v[152:153], v[194:195]
	v_pk_mul_f32 v[152:153], v[156:157], v[152:153]
	v_pk_fma_f32 v[156:157], v[130:131], v[186:187], v[190:191]
	v_exp_f32_e32 v140, v128
	v_pk_fma_f32 v[132:133], v[142:143], v[186:187], v[190:191]
	v_pk_fma_f32 v[156:157], v[134:135], v[182:183], v[156:157]
	v_pk_fma_f32 v[130:131], v[130:131], v[182:183], v[132:133]
	v_pk_fma_f32 v[154:155], v[154:155], v[178:179], v[156:157]
	v_pk_fma_f32 v[130:131], v[134:135], v[178:179], v[130:131]
	v_exp_f32_e32 v157, v154
	v_exp_f32_e32 v141, v129
	v_exp_f32_e32 v132, v130
	v_exp_f32_e32 v133, v131
	v_exp_f32_e32 v193, v155
	v_pk_add_f32 v[140:141], v[140:141], 1.0 op_sel_hi:[1,0]
	v_pk_add_f32 v[132:133], v[132:133], 1.0 op_sel_hi:[1,0]
	v_cvt_pk_bf16_f32 v253, v152, v153
	v_add_f32_e32 v152, 1.0, v157
	v_add_f32_e32 v153, 1.0, v193
	v_rcp_f32_e32 v140, v140
	v_rcp_f32_e32 v141, v141
; #define LAS __attribute__((address_space(3)))
; __device__ __forceinline__ float sigmoidf_(float x) { return __builtin_amdgcn_rcpf(1.0f + __expf(-x)); }
;     __device__ __forceinline__ void operator()(AccRef acc, const Unit& u, int wr, int wc, int fr, int fq) const {
;     ...
;                 f32x4 h2v = (f32x4){0.f, 0.f, 0.f, 0.f}, h3v = h2v, h2g = h2v, h3g = h2v;
;                 const int pb = ai * 2 + wr - 1;
;                 if (pb >= 0 && fr == 0) { const LAS float* xp = xch + (pb * 2) * 256 + clb + 4 * n;
;                     h2v = *(const LAS f32x4*)(xp); h3v = *(const LAS f32x4*)(xp + 256); h2g = *(const LAS f32x4*)(xp + 128); h3g = *(const LAS f32x4*)(xp + 256 + 128); }
;                 float o[4][4];
; #pragma unroll
;                 for (int j = 0; j < 4; ++j) {
;                     const float v0 = acc[ai][0][0][n][j], v1 = acc[ai][0][1][n][j], v2 = acc[ai][0][2][n][j], v3 = acc[ai][0][3][n][j];
;                     const float g0 = acc[ai][1][0][n][j], g1 = acc[ai][1][1][n][j], g2 = acc[ai][1][2][n][j], g3 = acc[ai][1][3][n][j];
;                     const float pv3 = dpp_upd<0x111>(h3v[j], v3), pv2 = dpp_upd<0x111>(h2v[j], v2), pg3 = dpp_upd<0x111>(h3g[j], g3), pg2 = dpp_upd<0x111>(h2g[j], g2);
;                     const float hv0 = bvv[j] + w2v[j] * v0 + w1v[j] * pv3 + w0v[j] * pv2, hv1 = bvv[j] + w2v[j] * v1 + w1v[j] * v0 + w0v[j] * pv3;
;                     const float hv2 = bvv[j] + w2v[j] * v2 + w1v[j] * v1 + w0v[j] * v0, hv3 = bvv[j] + w2v[j] * v3 + w1v[j] * v2 + w0v[j] * v1;
;                     const float hg0 = bvg[j] + w2g[j] * g0 + w1g[j] * pg3 + w0g[j] * pg2, hg1 = bvg[j] + w2g[j] * g1 + w1g[j] * g0 + w0g[j] * pg3;
;                     const float hg2 = bvg[j] + w2g[j] * g2 + w1g[j] * g1 + w0g[j] * g0, hg3 = bvg[j] + w2g[j] * g3 + w1g[j] * g2 + w0g[j] * g1;
;                     o[0][j] = hg0 * sigmoidf_(hg0) * hv0; o[1][j] = hg1 * sigmoidf_(hg1) * hv1; o[2][j] = hg2 * sigmoidf_(hg2) * hv2; o[3][j] = hg3 * sigmoidf_(hg3) * hv3; }
; #pragma unroll
;                 for (int m = 0; m < 4; ++m) { u32x2 w; w.x = cvt_pk_bf16(o[m][0], o[m][1]); w.y = cvt_pk_bf16(o[m][2], o[m][3]);
;                     *(u32x2*)(Aout + (size_t)(row0 + ai * 128 + m) * FH + hc0 + 4 * n) = w; } } }
	v_rcp_f32_e32 v132, v132
	v_rcp_f32_e32 v133, v133
	v_rcp_f32_e32 v152, v152
	v_rcp_f32_e32 v153, v153
	v_pk_fma_f32 v[142:143], v[150:151], v[170:171], v[174:175]
	v_pk_fma_f32 v[194:195], v[138:139], v[170:171], v[174:175]
	v_pk_fma_f32 v[136:137], v[136:137], v[164:165], v[148:149]
	v_pk_fma_f32 v[134:135], v[138:139], v[166:167], v[142:143]
	v_pk_fma_f32 v[194:195], v[146:147], v[166:167], v[194:195]
	v_pk_fma_f32 v[136:137], v[144:145], v[160:161], v[136:137]
	v_pk_mul_f32 v[128:129], v[128:129], v[140:141]
	v_pk_fma_f32 v[134:135], v[146:147], v[162:163], v[134:135]
	v_pk_mul_f32 v[130:131], v[130:131], v[132:133]
	v_pk_fma_f32 v[158:159], v[158:159], v[162:163], v[194:195]
	v_pk_mul_f32 v[152:153], v[154:155], v[152:153]
	v_pk_mul_f32 v[128:129], v[136:137], v[128:129]
	v_pk_mul_f32 v[130:131], v[134:135], v[130:131]
	v_pk_mul_f32 v[152:153], v[158:159], v[152:153]
	v_cvt_pk_bf16_f32 v250, v128, v129
	v_cvt_pk_bf16_f32 v251, v130, v131
	v_or_b32_e32 v130, 3, v245
	v_cvt_pk_bf16_f32 v254, v152, v153
	v_or_b32_e32 v152, 2, v245
	v_mad_i64_i32 v[130:131], s[34:35], v130, s63, v[206:207]
	v_mad_i64_i32 v[152:153], s[34:35], v152, s63, v[206:207]
	v_lshl_add_u64 v[140:141], v[130:131], 0, v[204:205]
	v_lshl_add_u64 v[152:153], v[152:153], 0, v[204:205]
	v_mov_b32_e32 v193, 0
	v_mov_b64_e32 v[194:195], 0
	v_mov_b64_e32 v[136:137], 0
	v_mov_b64_e32 v[138:139], 0
	v_mov_b64_e32 v[128:129], 0
	v_mov_b64_e32 v[130:131], 0
	v_mov_b64_e32 v[132:133], 0
	v_mov_b64_e32 v[134:135], 0
	s_barrier
	s_and_saveexec_b64 s[34:35], s[22:23]
	s_cbranch_execz .LBB0_1951
	ds_read_b128 v[132:135], v236 offset:2048
	ds_read_b128 v[136:139], v236 offset:2560
	ds_read_b128 v[128:131], v236 offset:3072
	ds_read_b128 v[192:195], v236 offset:3584
.LBB0_1951:
	s_or_b64 exec, exec, s[34:35]
	s_waitcnt lgkmcnt(0)
	v_mov_b32_dpp v192, v72 row_shr:1 row_mask:0xf bank_mask:0xf
	v_mov_b32_dpp v193, v73 row_shr:1 row_mask:0xf bank_mask:0xf
	v_pk_fma_f32 v[142:143], v[88:89], v[184:185], v[188:189]
	v_mov_b32_dpp v136, v64 row_shr:1 row_mask:0xf bank_mask:0xf
	v_mov_b32_dpp v137, v65 row_shr:1 row_mask:0xf bank_mask:0xf
	v_pk_fma_f32 v[142:143], v[180:181], v[192:193], v[142:143]
	v_mov_b32_dpp v128, v84 row_shr:1 row_mask:0xf bank_mask:0xf
	v_pk_fma_f32 v[136:137], v[176:177], v[136:137], v[142:143]
	v_mov_b32_dpp v129, v85 row_shr:1 row_mask:0xf bank_mask:0xf
	v_exp_f32_e32 v142, v136
	v_exp_f32_e32 v143, v137
	v_pk_fma_f32 v[144:145], v[92:93], v[168:169], v[172:173]
	v_mov_b32_dpp v132, v76 row_shr:1 row_mask:0xf bank_mask:0xf
	v_pk_add_f32 v[142:143], v[142:143], 1.0 op_sel_hi:[1,0]
	v_rcp_f32_e32 v142, v142
	v_rcp_f32_e32 v143, v143
	v_mov_b32_dpp v133, v77 row_shr:1 row_mask:0xf bank_mask:0xf
	v_pk_fma_f32 v[144:145], v[164:165], v[128:129], v[144:145]
	v_mov_b32_dpp v194, v74 row_shr:1 row_mask:0xf bank_mask:0xf
	v_pk_fma_f32 v[132:133], v[160:161], v[132:133], v[144:145]
	v_pk_mul_f32 v[136:137], v[136:137], v[142:143]
	v_mov_b32_dpp v195, v75 row_shr:1 row_mask:0xf bank_mask:0xf
	v_pk_mul_f32 v[132:133], v[132:133], v[136:137]
	v_pk_fma_f32 v[136:137], v[90:91], v[186:187], v[190:191]
	v_mov_b32_dpp v138, v66 row_shr:1 row_mask:0xf bank_mask:0xf
	v_mov_b32_dpp v139, v67 row_shr:1 row_mask:0xf bank_mask:0xf
	v_pk_fma_f32 v[136:137], v[182:183], v[194:195], v[136:137]
	v_mov_b32_dpp v130, v86 row_shr:1 row_mask:0xf bank_mask:0xf
	v_pk_fma_f32 v[136:137], v[178:179], v[138:139], v[136:137]
	v_mov_b32_dpp v131, v87 row_shr:1 row_mask:0xf bank_mask:0xf
	v_exp_f32_e32 v139, v136
	v_exp_f32_e32 v142, v137
	v_cvt_pk_bf16_f32 v144, v132, v133
	v_add_f32_e32 v132, 1.0, v139
	v_rcp_f32_e32 v132, v132
	v_add_f32_e32 v133, 1.0, v142
	v_rcp_f32_e32 v133, v133
	v_pk_fma_f32 v[142:143], v[94:95], v[170:171], v[174:175]
	v_mov_b32_dpp v134, v78 row_shr:1 row_mask:0xf bank_mask:0xf
	v_mov_b32_dpp v135, v79 row_shr:1 row_mask:0xf bank_mask:0xf
	v_pk_mul_f32 v[132:133], v[136:137], v[132:133]
	v_pk_fma_f32 v[136:137], v[68:69], v[184:185], v[188:189]
	v_pk_fma_f32 v[142:143], v[166:167], v[130:131], v[142:143]
	v_pk_fma_f32 v[136:137], v[88:89], v[180:181], v[136:137]
	v_pk_fma_f32 v[134:135], v[162:163], v[134:135], v[142:143]
	v_pk_fma_f32 v[136:137], v[176:177], v[192:193], v[136:137]
	v_add_u32_e32 v146, 0x80, v245
	v_exp_f32_e32 v142, v136
	v_exp_f32_e32 v143, v137
	v_pk_mul_f32 v[132:133], v[134:135], v[132:133]
	v_mov_b64_e32 v[134:135], s[60:61]
	v_cvt_pk_bf16_f32 v145, v132, v133
	v_mad_i64_i32 v[132:133], s[34:35], v146, s63, v[134:135]
	v_lshl_add_u64 v[132:133], v[132:133], 0, v[204:205]
	v_add_f32_e32 v138, 1.0, v142
	v_add_f32_e32 v139, 1.0, v143
	v_rcp_f32_e32 v138, v138
	v_rcp_f32_e32 v139, v139
	v_pk_fma_f32 v[142:143], v[80:81], v[168:169], v[172:173]
	v_pk_fma_f32 v[72:73], v[72:73], v[184:185], v[188:189]
	v_pk_fma_f32 v[142:143], v[92:93], v[164:165], v[142:143]
	v_pk_mul_f32 v[136:137], v[136:137], v[138:139]
	v_pk_fma_f32 v[128:129], v[160:161], v[128:129], v[142:143]
	v_pk_fma_f32 v[84:85], v[84:85], v[168:169], v[172:173]
	v_pk_mul_f32 v[128:129], v[128:129], v[136:137]
	v_pk_fma_f32 v[136:137], v[70:71], v[186:187], v[190:191]
	s_nop 0
	v_pk_fma_f32 v[136:137], v[90:91], v[182:183], v[136:137]
	s_nop 0
	v_pk_fma_f32 v[136:137], v[178:179], v[194:195], v[136:137]
	s_nop 0
	v_exp_f32_e32 v139, v136
	v_exp_f32_e32 v142, v137
	v_cvt_pk_bf16_f32 v138, v128, v129
	v_add_f32_e32 v128, 1.0, v139
	v_rcp_f32_e32 v128, v128
	v_add_f32_e32 v129, 1.0, v142
	v_rcp_f32_e32 v129, v129
	v_pk_fma_f32 v[142:143], v[82:83], v[170:171], v[174:175]
	v_pk_mul_f32 v[128:129], v[136:137], v[128:129]
	v_pk_fma_f32 v[142:143], v[94:95], v[166:167], v[142:143]
; #define LAS __attribute__((address_space(3)))
; __device__ __forceinline__ float sigmoidf_(float x) { return __builtin_amdgcn_rcpf(1.0f + __expf(-x)); }
;     __device__ __forceinline__ void operator()(AccRef acc, const Unit& u, int wr, int wc, int fr, int fq) const {
;     ...
;                 f32x4 h2v = (f32x4){0.f, 0.f, 0.f, 0.f}, h3v = h2v, h2g = h2v, h3g = h2v;
;                 const int pb = ai * 2 + wr - 1;
;                 if (pb >= 0 && fr == 0) { const LAS float* xp = xch + (pb * 2) * 256 + clb + 4 * n;
;                     h2v = *(const LAS f32x4*)(xp); h3v = *(const LAS f32x4*)(xp + 256); h2g = *(const LAS f32x4*)(xp + 128); h3g = *(const LAS f32x4*)(xp + 256 + 128); }
;                 float o[4][4];
; #pragma unroll
;                 for (int j = 0; j < 4; ++j) {
;                     const float v0 = acc[ai][0][0][n][j], v1 = acc[ai][0][1][n][j], v2 = acc[ai][0][2][n][j], v3 = acc[ai][0][3][n][j];
;                     const float g0 = acc[ai][1][0][n][j], g1 = acc[ai][1][1][n][j], g2 = acc[ai][1][2][n][j], g3 = acc[ai][1][3][n][j];
;                     const float pv3 = dpp_upd<0x111>(h3v[j], v3), pv2 = dpp_upd<0x111>(h2v[j], v2), pg3 = dpp_upd<0x111>(h3g[j], g3), pg2 = dpp_upd<0x111>(h2g[j], g2);
;                     const float hv0 = bvv[j] + w2v[j] * v0 + w1v[j] * pv3 + w0v[j] * pv2, hv1 = bvv[j] + w2v[j] * v1 + w1v[j] * v0 + w0v[j] * pv3;
;                     const float hv2 = bvv[j] + w2v[j] * v2 + w1v[j] * v1 + w0v[j] * v0, hv3 = bvv[j] + w2v[j] * v3 + w1v[j] * v2 + w0v[j] * v1;
;                     const float hg0 = bvg[j] + w2g[j] * g0 + w1g[j] * pg3 + w0g[j] * pg2, hg1 = bvg[j] + w2g[j] * g1 + w1g[j] * g0 + w0g[j] * pg3;
;                     const float hg2 = bvg[j] + w2g[j] * g2 + w1g[j] * g1 + w0g[j] * g0, hg3 = bvg[j] + w2g[j] * g3 + w1g[j] * g2 + w0g[j] * g1;
;                     o[0][j] = hg0 * sigmoidf_(hg0) * hv0; o[1][j] = hg1 * sigmoidf_(hg1) * hv1; o[2][j] = hg2 * sigmoidf_(hg2) * hv2; o[3][j] = hg3 * sigmoidf_(hg3) * hv3; }
; #pragma unroll
;                 for (int m = 0; m < 4; ++m) { u32x2 w; w.x = cvt_pk_bf16(o[m][0], o[m][1]); w.y = cvt_pk_bf16(o[m][2], o[m][3]);
;                     *(u32x2*)(Aout + (size_t)(row0 + ai * 128 + m) * FH + hc0 + 4 * n) = w; } } }
	v_pk_fma_f32 v[136:137], v[76:77], v[168:169], v[172:173]
	v_pk_fma_f32 v[130:131], v[162:163], v[130:131], v[142:143]
	v_pk_fma_f32 v[136:137], v[80:81], v[164:165], v[136:137]
	v_pk_mul_f32 v[128:129], v[130:131], v[128:129]
	v_pk_fma_f32 v[130:131], v[64:65], v[184:185], v[188:189]
	v_pk_fma_f32 v[64:65], v[64:65], v[180:181], v[72:73]
	v_pk_fma_f32 v[130:131], v[68:69], v[180:181], v[130:131]
	v_pk_fma_f32 v[64:65], v[68:69], v[176:177], v[64:65]
	v_pk_fma_f32 v[88:89], v[88:89], v[176:177], v[130:131]
	v_pk_fma_f32 v[92:93], v[92:93], v[160:161], v[136:137]
	v_exp_f32_e32 v130, v88
	v_exp_f32_e32 v131, v89
	v_exp_f32_e32 v72, v64
	v_pk_add_f32 v[130:131], v[130:131], 1.0 op_sel_hi:[1,0]
	v_rcp_f32_e32 v130, v130
	v_rcp_f32_e32 v131, v131
	v_pk_fma_f32 v[68:69], v[74:75], v[186:187], v[190:191]
	v_exp_f32_e32 v73, v65
	v_pk_mul_f32 v[88:89], v[88:89], v[130:131]
	v_pk_mul_f32 v[88:89], v[92:93], v[88:89]
	v_pk_fma_f32 v[92:93], v[66:67], v[186:187], v[190:191]
	v_pk_fma_f32 v[66:67], v[66:67], v[182:183], v[68:69]
	v_pk_fma_f32 v[92:93], v[70:71], v[182:183], v[92:93]
	v_pk_fma_f32 v[66:67], v[70:71], v[178:179], v[66:67]
	v_pk_fma_f32 v[90:91], v[90:91], v[178:179], v[92:93]
	v_exp_f32_e32 v93, v90
	v_exp_f32_e32 v68, v66
	v_exp_f32_e32 v69, v67
	v_exp_f32_e32 v130, v91
	v_pk_add_f32 v[72:73], v[72:73], 1.0 op_sel_hi:[1,0]
	v_pk_add_f32 v[68:69], v[68:69], 1.0 op_sel_hi:[1,0]
	v_cvt_pk_bf16_f32 v198, v88, v89
	v_add_f32_e32 v88, 1.0, v93
	v_add_f32_e32 v89, 1.0, v130
	v_rcp_f32_e32 v72, v72
	v_rcp_f32_e32 v73, v73
	v_rcp_f32_e32 v68, v68
	v_rcp_f32_e32 v69, v69
	v_rcp_f32_e32 v88, v88
	v_rcp_f32_e32 v89, v89
	v_pk_fma_f32 v[74:75], v[86:87], v[170:171], v[174:175]
	v_pk_fma_f32 v[130:131], v[78:79], v[170:171], v[174:175]
	v_pk_fma_f32 v[76:77], v[76:77], v[164:165], v[84:85]
	v_pk_fma_f32 v[70:71], v[78:79], v[166:167], v[74:75]
	v_pk_fma_f32 v[130:131], v[82:83], v[166:167], v[130:131]
	v_pk_fma_f32 v[76:77], v[80:81], v[160:161], v[76:77]
	v_pk_mul_f32 v[64:65], v[64:65], v[72:73]
	v_pk_fma_f32 v[70:71], v[82:83], v[162:163], v[70:71]
	v_pk_mul_f32 v[66:67], v[66:67], v[68:69]
	v_pk_fma_f32 v[94:95], v[94:95], v[162:163], v[130:131]
	v_pk_mul_f32 v[88:89], v[90:91], v[88:89]
	v_pk_mul_f32 v[64:65], v[76:77], v[64:65]
	v_pk_mul_f32 v[66:67], v[70:71], v[66:67]
	v_pk_mul_f32 v[88:89], v[94:95], v[88:89]
	v_cvt_pk_bf16_f32 v148, v64, v65
	v_cvt_pk_bf16_f32 v149, v66, v67
	v_add_u32_e32 v66, 0x83, v245
	v_cvt_pk_bf16_f32 v155, v128, v129
	v_add_u32_e32 v128, 0x81, v245
	v_cvt_pk_bf16_f32 v199, v88, v89
	v_add_u32_e32 v88, 0x82, v245
	v_mad_i64_i32 v[66:67], s[34:35], v66, s63, v[134:135]
	v_mad_i64_i32 v[128:129], s[34:35], v128, s63, v[134:135]
	v_mad_i64_i32 v[88:89], s[34:35], v88, s63, v[134:135]
	v_lshl_add_u64 v[82:83], v[66:67], 0, v[204:205]
	v_lshl_add_u64 v[128:129], v[128:129], 0, v[204:205]
	v_lshl_add_u64 v[88:89], v[88:89], 0, v[204:205]
	v_mov_b32_e32 v64, 0
	v_mov_b64_e32 v[70:71], 0
	v_mov_b64_e32 v[72:73], 0
	v_mov_b64_e32 v[78:79], 0
	v_mov_b64_e32 v[80:81], 0
	v_mov_b64_e32 v[66:67], 0
	v_mov_b64_e32 v[68:69], 0
	v_mov_b64_e32 v[74:75], 0
	v_mov_b64_e32 v[76:77], 0
	v_mov_b32_e32 v154, v138
	s_barrier
	s_and_saveexec_b64 s[34:35], s[20:21]
	s_cbranch_execz .LBB0_1953
	ds_read_b128 v[74:77], v241
	ds_read_b128 v[66:69], v240
	ds_read_b128 v[78:81], v239
	ds_read_b128 v[70:73], v238
; #define LAS __attribute__((address_space(3)))
; __device__ __forceinline__ float sigmoidf_(float x) { return __builtin_amdgcn_rcpf(1.0f + __expf(-x)); }
;     __device__ __forceinline__ void operator()(AccRef acc, const Unit& u, int wr, int wc, int fr, int fq) const {
;     ...
;                 f32x4 h2v = (f32x4){0.f, 0.f, 0.f, 0.f}, h3v = h2v, h2g = h2v, h3g = h2v;
;                 const int pb = ai * 2 + wr - 1;
;                 if (pb >= 0 && fr == 0) { const LAS float* xp = xch + (pb * 2) * 256 + clb + 4 * n;
;                     h2v = *(const LAS f32x4*)(xp); h3v = *(const LAS f32x4*)(xp + 256); h2g = *(const LAS f32x4*)(xp + 128); h3g = *(const LAS f32x4*)(xp + 256 + 128); }
;                 float o[4][4];
; #pragma unroll
;                 for (int j = 0; j < 4; ++j) {
;                     const float v0 = acc[ai][0][0][n][j], v1 = acc[ai][0][1][n][j], v2 = acc[ai][0][2][n][j], v3 = acc[ai][0][3][n][j];
;                     const float g0 = acc[ai][1][0][n][j], g1 = acc[ai][1][1][n][j], g2 = acc[ai][1][2][n][j], g3 = acc[ai][1][3][n][j];
;                     const float pv3 = dpp_upd<0x111>(h3v[j], v3), pv2 = dpp_upd<0x111>(h2v[j], v2), pg3 = dpp_upd<0x111>(h3g[j], g3), pg2 = dpp_upd<0x111>(h2g[j], g2);
;                     const float hv0 = bvv[j] + w2v[j] * v0 + w1v[j] * pv3 + w0v[j] * pv2, hv1 = bvv[j] + w2v[j] * v1 + w1v[j] * v0 + w0v[j] * pv3;
;                     const float hv2 = bvv[j] + w2v[j] * v2 + w1v[j] * v1 + w0v[j] * v0, hv3 = bvv[j] + w2v[j] * v3 + w1v[j] * v2 + w0v[j] * v1;
;                     const float hg0 = bvg[j] + w2g[j] * g0 + w1g[j] * pg3 + w0g[j] * pg2, hg1 = bvg[j] + w2g[j] * g1 + w1g[j] * g0 + w0g[j] * pg3;
;                     const float hg2 = bvg[j] + w2g[j] * g2 + w1g[j] * g1 + w0g[j] * g0, hg3 = bvg[j] + w2g[j] * g3 + w1g[j] * g2 + w0g[j] * g1;
;                     o[0][j] = hg0 * sigmoidf_(hg0) * hv0; o[1][j] = hg1 * sigmoidf_(hg1) * hv1; o[2][j] = hg2 * sigmoidf_(hg2) * hv2; o[3][j] = hg3 * sigmoidf_(hg3) * hv3; }
; #pragma unroll
;                 for (int m = 0; m < 4; ++m) { u32x2 w; w.x = cvt_pk_bf16(o[m][0], o[m][1]); w.y = cvt_pk_bf16(o[m][2], o[m][3]);
;                     *(u32x2*)(Aout + (size_t)(row0 + ai * 128 + m) * FH + hc0 + 4 * n) = w; } } }
.LBB0_1953:
	s_or_b64 exec, exec, s[34:35]
	s_waitcnt lgkmcnt(0)
	v_mov_b32_dpp v70, v44 row_shr:1 row_mask:0xf bank_mask:0xf
	v_mov_b32_dpp v71, v45 row_shr:1 row_mask:0xf bank_mask:0xf
	s_waitcnt vmcnt(0)
	v_pk_fma_f32 v[84:85], v[56:57], v[120:121], v[124:125]
	v_mov_b32_dpp v78, v32 row_shr:1 row_mask:0xf bank_mask:0xf
	v_mov_b32_dpp v79, v33 row_shr:1 row_mask:0xf bank_mask:0xf
	v_pk_fma_f32 v[84:85], v[116:117], v[70:71], v[84:85]
	v_mov_b32_dpp v66, v52 row_shr:1 row_mask:0xf bank_mask:0xf
	v_pk_fma_f32 v[78:79], v[112:113], v[78:79], v[84:85]
	v_mov_b32_dpp v67, v53 row_shr:1 row_mask:0xf bank_mask:0xf
	v_exp_f32_e32 v84, v78
	v_exp_f32_e32 v85, v79
	v_pk_fma_f32 v[86:87], v[60:61], v[104:105], v[108:109]
	v_pk_add_f32 v[84:85], v[84:85], 1.0 op_sel_hi:[1,0]
	v_rcp_f32_e32 v84, v84
	v_rcp_f32_e32 v85, v85
	v_mov_b32_dpp v74, v40 row_shr:1 row_mask:0xf bank_mask:0xf
	v_mov_b32_dpp v75, v41 row_shr:1 row_mask:0xf bank_mask:0xf
	v_pk_fma_f32 v[86:87], v[100:101], v[66:67], v[86:87]
	v_pk_mul_f32 v[78:79], v[78:79], v[84:85]
	v_pk_fma_f32 v[74:75], v[96:97], v[74:75], v[86:87]
	v_mov_b32_dpp v72, v46 row_shr:1 row_mask:0xf bank_mask:0xf
	v_mov_b32_dpp v73, v47 row_shr:1 row_mask:0xf bank_mask:0xf
	v_pk_mul_f32 v[74:75], v[74:75], v[78:79]
	v_pk_fma_f32 v[78:79], v[58:59], v[122:123], v[126:127]
	v_mov_b32_dpp v80, v34 row_shr:1 row_mask:0xf bank_mask:0xf
	v_mov_b32_dpp v81, v35 row_shr:1 row_mask:0xf bank_mask:0xf
	v_pk_fma_f32 v[78:79], v[118:119], v[72:73], v[78:79]
	v_mov_b32_dpp v68, v54 row_shr:1 row_mask:0xf bank_mask:0xf
	v_pk_fma_f32 v[78:79], v[114:115], v[80:81], v[78:79]
	v_mov_b32_dpp v69, v55 row_shr:1 row_mask:0xf bank_mask:0xf
	v_exp_f32_e32 v80, v78
	v_exp_f32_e32 v81, v79
	v_pk_fma_f32 v[84:85], v[62:63], v[106:107], v[110:111]
	v_pk_add_f32 v[80:81], v[80:81], 1.0 op_sel_hi:[1,0]
	v_rcp_f32_e32 v80, v80
	v_rcp_f32_e32 v81, v81
	v_mov_b32_dpp v76, v42 row_shr:1 row_mask:0xf bank_mask:0xf
	v_mov_b32_dpp v77, v43 row_shr:1 row_mask:0xf bank_mask:0xf
	v_pk_fma_f32 v[84:85], v[102:103], v[68:69], v[84:85]
	v_pk_mul_f32 v[78:79], v[78:79], v[80:81]
	v_pk_fma_f32 v[76:77], v[98:99], v[76:77], v[84:85]
	v_cvt_pk_bf16_f32 v92, v74, v75
	v_pk_mul_f32 v[76:77], v[76:77], v[78:79]
	v_pk_fma_f32 v[44:45], v[44:45], v[120:121], v[124:125]
	v_cvt_pk_bf16_f32 v93, v76, v77
	v_pk_fma_f32 v[76:77], v[36:37], v[120:121], v[124:125]
	v_mov_b32_e32 v90, v246
	v_mov_b32_e32 v91, v247
	global_store_dwordx4 v[202:203], v[90:93], off
	v_pk_fma_f32 v[76:77], v[56:57], v[116:117], v[76:77]
	v_pk_fma_f32 v[52:53], v[52:53], v[104:105], v[108:109]
	v_pk_fma_f32 v[70:71], v[112:113], v[70:71], v[76:77]
	s_nop 0
	v_exp_f32_e32 v74, v70
	v_exp_f32_e32 v75, v71
	s_nop 0
	v_pk_add_f32 v[74:75], v[74:75], 1.0 op_sel_hi:[1,0]
	v_rcp_f32_e32 v74, v74
	v_rcp_f32_e32 v75, v75
	v_pk_fma_f32 v[76:77], v[48:49], v[104:105], v[108:109]
	v_pk_mul_f32 v[70:71], v[70:71], v[74:75]
	v_pk_fma_f32 v[76:77], v[60:61], v[100:101], v[76:77]
	v_pk_fma_f32 v[74:75], v[50:51], v[106:107], v[110:111]
	v_pk_fma_f32 v[66:67], v[96:97], v[66:67], v[76:77]
	v_pk_fma_f32 v[74:75], v[62:63], v[102:103], v[74:75]
	v_pk_mul_f32 v[66:67], v[66:67], v[70:71]
	v_pk_fma_f32 v[70:71], v[38:39], v[122:123], v[126:127]
	v_pk_fma_f32 v[68:69], v[98:99], v[68:69], v[74:75]
	v_pk_fma_f32 v[70:71], v[58:59], v[118:119], v[70:71]
	v_cvt_pk_bf16_f32 v136, v66, v67
	v_pk_fma_f32 v[70:71], v[114:115], v[72:73], v[70:71]
	s_nop 0
	v_exp_f32_e32 v72, v70
	v_exp_f32_e32 v73, v71
	s_nop 0
	v_pk_add_f32 v[72:73], v[72:73], 1.0 op_sel_hi:[1,0]
	v_rcp_f32_e32 v72, v72
	v_rcp_f32_e32 v73, v73
	s_nop 0
	v_pk_mul_f32 v[70:71], v[70:71], v[72:73]
	s_nop 0
	v_pk_mul_f32 v[68:69], v[68:69], v[70:71]
	s_nop 0
	v_cvt_pk_bf16_f32 v137, v68, v69
	v_pk_fma_f32 v[68:69], v[32:33], v[120:121], v[124:125]
	v_mov_b32_e32 v134, v248
	v_mov_b32_e32 v135, v249
	global_store_dwordx4 v[196:197], v[134:137], off
	v_pk_fma_f32 v[68:69], v[36:37], v[116:117], v[68:69]
	v_pk_fma_f32 v[32:33], v[32:33], v[116:117], v[44:45]
	v_pk_fma_f32 v[56:57], v[56:57], v[112:113], v[68:69]
	v_pk_fma_f32 v[32:33], v[36:37], v[112:113], v[32:33]
	v_exp_f32_e32 v66, v56
	v_exp_f32_e32 v67, v57
	s_nop 0
	v_pk_add_f32 v[66:67], v[66:67], 1.0 op_sel_hi:[1,0]
	v_rcp_f32_e32 v66, v66
	v_rcp_f32_e32 v67, v67
	v_pk_fma_f32 v[68:69], v[40:41], v[104:105], v[108:109]
	v_exp_f32_e32 v44, v32
	v_pk_fma_f32 v[68:69], v[48:49], v[100:101], v[68:69]
	v_pk_mul_f32 v[56:57], v[56:57], v[66:67]
	v_pk_fma_f32 v[60:61], v[60:61], v[96:97], v[68:69]
	v_pk_fma_f32 v[36:37], v[46:47], v[122:123], v[126:127]
	v_pk_mul_f32 v[56:57], v[60:61], v[56:57]
	v_pk_fma_f32 v[60:61], v[34:35], v[122:123], v[126:127]
	v_pk_fma_f32 v[34:35], v[34:35], v[118:119], v[36:37]
	v_pk_fma_f32 v[60:61], v[38:39], v[118:119], v[60:61]
	v_pk_fma_f32 v[34:35], v[38:39], v[114:115], v[34:35]
	v_pk_fma_f32 v[58:59], v[58:59], v[114:115], v[60:61]
	v_exp_f32_e32 v60, v58
	v_exp_f32_e32 v45, v33
	v_exp_f32_e32 v36, v34
	v_exp_f32_e32 v37, v35
	v_exp_f32_e32 v61, v59
	v_cvt_pk_bf16_f32 v164, v56, v57
	v_pk_add_f32 v[44:45], v[44:45], 1.0 op_sel_hi:[1,0]
	v_pk_add_f32 v[36:37], v[36:37], 1.0 op_sel_hi:[1,0]
	v_pk_add_f32 v[60:61], v[60:61], 1.0 op_sel_hi:[1,0]
	v_rcp_f32_e32 v44, v44
	v_rcp_f32_e32 v45, v45
	v_rcp_f32_e32 v36, v36
	v_rcp_f32_e32 v37, v37
	v_rcp_f32_e32 v60, v60
	v_rcp_f32_e32 v61, v61
	v_pk_fma_f32 v[46:47], v[54:55], v[106:107], v[110:111]
	v_pk_fma_f32 v[66:67], v[42:43], v[106:107], v[110:111]
	v_pk_fma_f32 v[40:41], v[40:41], v[100:101], v[52:53]
	v_pk_fma_f32 v[38:39], v[42:43], v[102:103], v[46:47]
	v_pk_fma_f32 v[66:67], v[50:51], v[102:103], v[66:67]
	v_pk_fma_f32 v[40:41], v[48:49], v[96:97], v[40:41]
	v_pk_mul_f32 v[32:33], v[32:33], v[44:45]
	v_pk_fma_f32 v[38:39], v[50:51], v[98:99], v[38:39]
	v_pk_mul_f32 v[34:35], v[34:35], v[36:37]
	v_pk_fma_f32 v[62:63], v[62:63], v[98:99], v[66:67]
	v_pk_mul_f32 v[58:59], v[58:59], v[60:61]
	v_pk_mul_f32 v[32:33], v[40:41], v[32:33]
	v_pk_mul_f32 v[34:35], v[38:39], v[34:35]
	v_pk_mul_f32 v[58:59], v[62:63], v[58:59]
	v_cvt_pk_bf16_f32 v160, v32, v33
	v_cvt_pk_bf16_f32 v161, v34, v35
	v_cvt_pk_bf16_f32 v165, v58, v59
	v_mov_b32_e32 v158, v250
	v_mov_b32_e32 v159, v251
	global_store_dwordx4 v[140:141], v[158:161], off
	v_mov_b32_e32 v65, 0
	v_mov_b64_e32 v[66:67], 0
	v_mov_b64_e32 v[40:41], 0
	v_mov_b64_e32 v[42:43], 0
	v_mov_b64_e32 v[32:33], 0
	v_mov_b64_e32 v[34:35], 0
	v_mov_b64_e32 v[36:37], 0
	v_mov_b64_e32 v[38:39], 0
	v_mov_b32_e32 v162, v253
	v_mov_b32_e32 v163, v254
	global_store_dwordx4 v[152:153], v[162:165], off
	s_barrier
	s_and_saveexec_b64 s[34:35], s[22:23]
	s_cbranch_execz .LBB0_1936
	ds_read_b128 v[36:39], v236 offset:2064
	ds_read_b128 v[40:43], v236 offset:2576
	ds_read_b128 v[32:35], v236 offset:3088
	ds_read_b128 v[64:67], v236 offset:3600
	s_branch .LBB0_1936
